# select_rows candidate compaction: running offset kept in an SGPR instead of a per-wave LDS atomic counter (no LDS round trip per slot)
# speedup vs baseline: 1.0145x; 1.0009x over previous
; #define LAS __attribute__((address_space(3)))
; #define GAS __attribute__((address_space(1)))
; __device__ __forceinline__ unsigned skey_of(float f) { const unsigned u = __float_as_uint(f); return u ^ ((unsigned)((int)u >> 31) | 0x80000000u); }
; template <int NJ>
; __device__ __forceinline__ void select_rows(const GAS float* sr0, GAS unsigned long long* mb0, LAS unsigned* hist, LAS unsigned* kbuf, int ntl, int lane) {
;     ...
;     for (int rr = 0; rr < 8; ++rr) {
;         const GAS float* srow = sr0 + (size_t)rr * SEQ;
;         float fv[NJ];
; #pragma unroll
;         for (int j = 0; j < NJ; ++j) fv[j] = srow[64 * j];
;         { unsigned z = 0u; asm volatile("" : "+v"(z));
;           *(LAS u32x4*)(hist + 4 * lane) = (u32x4){z, z, z, z}; if (lane < 2) hist[256 + lane] = z; }
;         __builtin_amdgcn_wave_barrier();
;         unsigned key[NJ];
; #pragma unroll
;         for (int j = 0; j < NJ; ++j) {
;             const float f = fv[j]; const bool ok = (vm >> j) & 1u;
;             key[j] = ok ? skey_of(f) : 0u;
;             const int bk = min(max((int)floorf(f + f) + 128, 0), 255);
;             __hip_atomic_fetch_add(hist + (ok ? bk : 256), 1u, __ATOMIC_RELAXED, __HIP_MEMORY_SCOPE_WORKGROUP);
.LBB0_382:
	s_mov_b32 s100, 0
	s_lshl_b32 s88, s12, 11
	v_lshl_add_u64 v[2:3], s[88:89], 2, v[8:9]
	s_movk_i32 s0, 0x1000
	s_add_i32 s98, s88, 0x800
	s_mov_b32 s99, s89
	s_waitcnt vmcnt(1)
	v_mov_b32_e32 v45, v51
	v_mov_b32_e32 v10, v52
	v_mov_b32_e32 v11, v53
	v_mov_b32_e32 v12, v54
	v_mov_b32_e32 v13, v55
	v_mov_b32_e32 v14, v56
	v_mov_b32_e32 v15, v57
	v_mov_b32_e32 v16, v58
	v_mov_b32_e32 v17, v59
	v_mov_b32_e32 v18, v60
	v_mov_b32_e32 v19, v61
	v_mov_b32_e32 v20, v62
	v_mov_b32_e32 v21, v63
	v_mov_b32_e32 v22, v64
	v_mov_b32_e32 v23, v65
	v_mov_b32_e32 v24, v66
	v_mov_b32_e32 v25, v67
	v_mov_b32_e32 v26, v68
	v_mov_b32_e32 v27, v69
	v_mov_b32_e32 v28, v70
	v_mov_b32_e32 v29, v71
	v_mov_b32_e32 v30, v72
	v_mov_b32_e32 v31, v73
	v_mov_b32_e32 v32, v74
	v_mov_b32_e32 v33, v75
	v_mov_b32_e32 v34, v76
	v_mov_b32_e32 v35, v77
	v_mov_b32_e32 v36, v78
	v_mov_b32_e32 v37, v79
	v_mov_b32_e32 v42, v80
	v_mov_b32_e32 v43, v81
	v_mov_b32_e32 v44, v82
	v_lshl_add_u64 v[84:85], s[98:99], 2, v[8:9]
	v_add_co_u32_e32 v86, vcc, 0x1000, v84
	s_nop 1
	v_addc_co_u32_e32 v87, vcc, 0, v85, vcc
	global_load_dword v51, v[84:85], off
	global_load_dword v52, v[84:85], off offset:256
	global_load_dword v53, v[84:85], off offset:512
	global_load_dword v54, v[84:85], off offset:768
	global_load_dword v55, v[84:85], off offset:1024
	global_load_dword v56, v[84:85], off offset:1280
	global_load_dword v57, v[84:85], off offset:1536
	global_load_dword v58, v[84:85], off offset:1792
	global_load_dword v59, v[84:85], off offset:2048
	global_load_dword v60, v[84:85], off offset:2304
	global_load_dword v61, v[84:85], off offset:2560
	global_load_dword v62, v[84:85], off offset:2816
	global_load_dword v63, v[84:85], off offset:3072
	global_load_dword v64, v[84:85], off offset:3328
	global_load_dword v65, v[84:85], off offset:3584
	global_load_dword v66, v[84:85], off offset:3840
	global_load_dword v67, v[86:87], off
	global_load_dword v68, v[86:87], off offset:256
	global_load_dword v69, v[86:87], off offset:512
	global_load_dword v70, v[86:87], off offset:768
	global_load_dword v71, v[86:87], off offset:1024
	global_load_dword v72, v[86:87], off offset:1280
	global_load_dword v73, v[86:87], off offset:1536
	global_load_dword v74, v[86:87], off offset:1792
	global_load_dword v75, v[86:87], off offset:2048
	global_load_dword v76, v[86:87], off offset:2304
	global_load_dword v77, v[86:87], off offset:2560
	global_load_dword v78, v[86:87], off offset:2816
	global_load_dword v79, v[86:87], off offset:3072
	global_load_dword v80, v[86:87], off offset:3328
	global_load_dword v81, v[86:87], off offset:3584
	global_load_dword v82, v[86:87], off offset:3840
	v_mov_b32_e32 v2, 0
	s_nop 0
	v_mov_b32_e32 v3, v2
	v_mov_b32_e32 v4, v2
	v_mov_b32_e32 v5, v2
	ds_write_b128 v7, v[2:5]
	s_and_saveexec_b64 s[0:1], s[74:75]
	v_add_u32_e32 v3, v7, v38
	ds_write_b32 v3, v2 offset:1024
	s_or_b64 exec, exec, s[0:1]
	v_add_f32_e32 v2, v45, v45
	v_floor_f32_e32 v2, v2
	v_cvt_i32_f32_e32 v2, v2
	v_add_f32_e32 v3, v10, v10
	v_floor_f32_e32 v3, v3
	v_cvt_i32_f32_e32 v3, v3
	v_max_i32_e32 v2, 0xffffff80, v2
	v_add_u32_e32 v2, 0x80, v2
	v_min_u32_e32 v2, 0xff, v2
	v_cndmask_b32_e64 v2, v2, v226, s[94:95]
	v_lshl_add_u32 v2, v2, 2, s6
	ds_add_u32 v2, v223
	v_max_i32_e32 v2, 0xffffff80, v3
	v_add_f32_e32 v3, v11, v11
	v_floor_f32_e32 v3, v3
	v_add_u32_e32 v2, 0x80, v2
	v_cvt_i32_f32_e32 v3, v3
	v_min_u32_e32 v2, 0xff, v2
	v_cndmask_b32_e64 v2, v2, v226, s[14:15]
	v_lshl_add_u32 v2, v2, 2, s6
	ds_add_u32 v2, v223
	v_max_i32_e32 v2, 0xffffff80, v3
	v_add_f32_e32 v3, v12, v12
	v_floor_f32_e32 v3, v3
	v_add_u32_e32 v2, 0x80, v2
	v_cvt_i32_f32_e32 v3, v3
	v_min_u32_e32 v2, 0xff, v2
	v_cndmask_b32_e64 v2, v2, v226, s[16:17]
	v_lshl_add_u32 v2, v2, 2, s6
	ds_add_u32 v2, v223
	v_max_i32_e32 v2, 0xffffff80, v3
	v_add_f32_e32 v3, v13, v13
	v_floor_f32_e32 v3, v3
	v_add_u32_e32 v2, 0x80, v2
	v_cvt_i32_f32_e32 v3, v3
	v_min_u32_e32 v2, 0xff, v2
	v_cndmask_b32_e64 v2, v2, v226, s[18:19]
	v_lshl_add_u32 v2, v2, 2, s6
	ds_add_u32 v2, v223
	v_max_i32_e32 v2, 0xffffff80, v3
	v_add_f32_e32 v3, v14, v14
	v_floor_f32_e32 v3, v3
	v_add_u32_e32 v2, 0x80, v2
	v_cvt_i32_f32_e32 v3, v3
	v_min_u32_e32 v2, 0xff, v2
	v_cndmask_b32_e64 v2, v2, v226, s[24:25]
	v_lshl_add_u32 v2, v2, 2, s6
	ds_add_u32 v2, v223
	v_max_i32_e32 v2, 0xffffff80, v3
	v_add_f32_e32 v3, v15, v15
	v_floor_f32_e32 v3, v3
	v_add_u32_e32 v2, 0x80, v2
	v_cvt_i32_f32_e32 v3, v3
	v_min_u32_e32 v2, 0xff, v2
	v_cndmask_b32_e64 v2, v2, v226, s[26:27]
	v_lshl_add_u32 v2, v2, 2, s6
	ds_add_u32 v2, v223
	v_max_i32_e32 v2, 0xffffff80, v3
	v_add_f32_e32 v3, v16, v16
	v_floor_f32_e32 v3, v3
	v_add_u32_e32 v2, 0x80, v2
	v_cvt_i32_f32_e32 v3, v3
	v_min_u32_e32 v2, 0xff, v2
	v_cndmask_b32_e64 v2, v2, v226, s[28:29]
	v_lshl_add_u32 v2, v2, 2, s6
	ds_add_u32 v2, v223
	v_max_i32_e32 v2, 0xffffff80, v3
	v_add_f32_e32 v3, v17, v17
	v_floor_f32_e32 v3, v3
	v_add_u32_e32 v2, 0x80, v2
	v_cvt_i32_f32_e32 v3, v3
	v_min_u32_e32 v2, 0xff, v2
	v_cndmask_b32_e64 v2, v2, v226, s[30:31]
	v_lshl_add_u32 v2, v2, 2, s6
	ds_add_u32 v2, v223
	v_max_i32_e32 v2, 0xffffff80, v3
	v_add_f32_e32 v3, v18, v18
	v_floor_f32_e32 v3, v3
	v_add_u32_e32 v2, 0x80, v2
	v_cvt_i32_f32_e32 v3, v3
	v_min_u32_e32 v2, 0xff, v2
	v_cndmask_b32_e64 v2, v2, v226, s[34:35]
	v_lshl_add_u32 v2, v2, 2, s6
	ds_add_u32 v2, v223
	v_max_i32_e32 v2, 0xffffff80, v3
	v_add_f32_e32 v3, v19, v19
	v_floor_f32_e32 v3, v3
	v_add_u32_e32 v2, 0x80, v2
	v_cvt_i32_f32_e32 v3, v3
	v_min_u32_e32 v2, 0xff, v2
	v_cndmask_b32_e64 v2, v2, v226, s[36:37]
	v_lshl_add_u32 v2, v2, 2, s6
	ds_add_u32 v2, v223
	v_max_i32_e32 v2, 0xffffff80, v3
; #define LAS __attribute__((address_space(3)))
; __device__ __forceinline__ unsigned skey_of(float f) { const unsigned u = __float_as_uint(f); return u ^ ((unsigned)((int)u >> 31) | 0x80000000u); }
; template <int NJ>
; __device__ __forceinline__ void select_rows(const GAS float* sr0, GAS unsigned long long* mb0, LAS unsigned* hist, LAS unsigned* kbuf, int ntl, int lane) {
;     ...
; #pragma unroll
;         for (int j = 0; j < NJ; ++j) {
;             const float f = fv[j]; const bool ok = (vm >> j) & 1u;
;             key[j] = ok ? skey_of(f) : 0u;
;             const int bk = min(max((int)floorf(f + f) + 128, 0), 255);
;             __hip_atomic_fetch_add(hist + (ok ? bk : 256), 1u, __ATOMIC_RELAXED, __HIP_MEMORY_SCOPE_WORKGROUP);
;         }
;         __builtin_amdgcn_wave_barrier();
;         asm volatile("s_waitcnt lgkmcnt(0)" ::: "memory");
;         unsigned B, rem, C;
;         {
;             const u32x4 hv = *(const LAS u32x4*)(hist + 4 * lane);
;             const unsigned s4 = hv.x + hv.y + hv.z + hv.w;
;             unsigned S = s4;
; #pragma unroll
;             for (int off = 1; off < 64; off <<= 1) { const unsigned n = __shfl_down(S, off); if (lane + off < 64) S += n; }
;             const unsigned excl = S - s4;
;             const bool mine = (excl < 256u) && (256u <= S);
;             unsigned dl, above, cnt, c = excl;
;             if (c + hv.w >= 256u) { dl = 3; above = c; cnt = hv.w; } else { c += hv.w; if (c + hv.z >= 256u) { dl = 2; above = c; cnt = hv.z; } else { c += hv.z; if (c + hv.y >= 256u) { dl = 1; above = c; cnt = hv.y; } else { c += hv.y; dl = 0; above = c; cnt = hv.x; } } }
	v_add_f32_e32 v3, v20, v20
	v_floor_f32_e32 v3, v3
	v_add_u32_e32 v2, 0x80, v2
	v_cvt_i32_f32_e32 v3, v3
	v_min_u32_e32 v2, 0xff, v2
	v_cndmask_b32_e64 v2, v2, v226, s[38:39]
	v_lshl_add_u32 v2, v2, 2, s6
	ds_add_u32 v2, v223
	v_max_i32_e32 v2, 0xffffff80, v3
	v_add_f32_e32 v3, v21, v21
	v_floor_f32_e32 v3, v3
	v_add_u32_e32 v2, 0x80, v2
	v_cvt_i32_f32_e32 v3, v3
	v_min_u32_e32 v2, 0xff, v2
	v_cndmask_b32_e64 v2, v2, v226, s[40:41]
	v_lshl_add_u32 v2, v2, 2, s6
	ds_add_u32 v2, v223
	v_max_i32_e32 v2, 0xffffff80, v3
	v_add_f32_e32 v3, v22, v22
	v_floor_f32_e32 v3, v3
	v_add_u32_e32 v2, 0x80, v2
	v_cvt_i32_f32_e32 v3, v3
	v_min_u32_e32 v2, 0xff, v2
	v_cndmask_b32_e64 v2, v2, v226, s[42:43]
	v_lshl_add_u32 v2, v2, 2, s6
	ds_add_u32 v2, v223
	v_max_i32_e32 v2, 0xffffff80, v3
	v_add_f32_e32 v3, v23, v23
	v_floor_f32_e32 v3, v3
	v_add_u32_e32 v2, 0x80, v2
	v_cvt_i32_f32_e32 v3, v3
	v_min_u32_e32 v2, 0xff, v2
	v_cndmask_b32_e64 v2, v2, v226, s[44:45]
	v_lshl_add_u32 v2, v2, 2, s6
	ds_add_u32 v2, v223
	v_max_i32_e32 v2, 0xffffff80, v3
	v_add_f32_e32 v3, v24, v24
	v_floor_f32_e32 v3, v3
	v_add_u32_e32 v2, 0x80, v2
	v_cvt_i32_f32_e32 v3, v3
	v_min_u32_e32 v2, 0xff, v2
	v_cndmask_b32_e64 v2, v2, v226, s[46:47]
	v_lshl_add_u32 v2, v2, 2, s6
	ds_add_u32 v2, v223
	v_max_i32_e32 v2, 0xffffff80, v3
	v_add_f32_e32 v3, v25, v25
	v_floor_f32_e32 v3, v3
	v_add_u32_e32 v2, 0x80, v2
	v_cvt_i32_f32_e32 v3, v3
	v_min_u32_e32 v2, 0xff, v2
	v_cndmask_b32_e64 v2, v2, v226, s[48:49]
	v_lshl_add_u32 v2, v2, 2, s6
	ds_add_u32 v2, v223
	v_max_i32_e32 v2, 0xffffff80, v3
	v_add_f32_e32 v3, v26, v26
	v_floor_f32_e32 v3, v3
	v_add_u32_e32 v2, 0x80, v2
	v_cvt_i32_f32_e32 v3, v3
	v_min_u32_e32 v2, 0xff, v2
	v_cndmask_b32_e64 v2, v2, v226, s[50:51]
	v_lshl_add_u32 v2, v2, 2, s6
	ds_add_u32 v2, v223
	v_max_i32_e32 v2, 0xffffff80, v3
	v_add_f32_e32 v3, v27, v27
	v_floor_f32_e32 v3, v3
	v_add_u32_e32 v2, 0x80, v2
	v_cvt_i32_f32_e32 v3, v3
	v_min_u32_e32 v2, 0xff, v2
	v_cndmask_b32_e64 v2, v2, v226, s[52:53]
	v_lshl_add_u32 v2, v2, 2, s6
	ds_add_u32 v2, v223
	v_max_i32_e32 v2, 0xffffff80, v3
	v_add_f32_e32 v3, v28, v28
	v_floor_f32_e32 v3, v3
	v_add_u32_e32 v2, 0x80, v2
	v_cvt_i32_f32_e32 v3, v3
	v_min_u32_e32 v2, 0xff, v2
	v_cndmask_b32_e64 v2, v2, v226, s[54:55]
	v_lshl_add_u32 v2, v2, 2, s6
	ds_add_u32 v2, v223
	v_max_i32_e32 v2, 0xffffff80, v3
	v_add_f32_e32 v3, v29, v29
	v_floor_f32_e32 v3, v3
	v_add_u32_e32 v2, 0x80, v2
	v_cvt_i32_f32_e32 v3, v3
	v_min_u32_e32 v2, 0xff, v2
	v_cndmask_b32_e64 v2, v2, v226, s[64:65]
	v_lshl_add_u32 v2, v2, 2, s6
	ds_add_u32 v2, v223
	v_max_i32_e32 v2, 0xffffff80, v3
	v_add_f32_e32 v3, v30, v30
	v_floor_f32_e32 v3, v3
	v_add_u32_e32 v2, 0x80, v2
	v_cvt_i32_f32_e32 v3, v3
	v_min_u32_e32 v2, 0xff, v2
	v_cndmask_b32_e64 v2, v2, v226, s[66:67]
	v_lshl_add_u32 v2, v2, 2, s6
	ds_add_u32 v2, v223
	v_max_i32_e32 v2, 0xffffff80, v3
	v_add_f32_e32 v3, v31, v31
	v_floor_f32_e32 v3, v3
	v_add_u32_e32 v2, 0x80, v2
	v_cvt_i32_f32_e32 v3, v3
	v_min_u32_e32 v2, 0xff, v2
	v_cndmask_b32_e64 v2, v2, v226, s[70:71]
	v_lshl_add_u32 v2, v2, 2, s6
	ds_add_u32 v2, v223
	v_max_i32_e32 v2, 0xffffff80, v3
	v_add_f32_e32 v3, v32, v32
	v_floor_f32_e32 v3, v3
	v_add_u32_e32 v2, 0x80, v2
	v_cvt_i32_f32_e32 v3, v3
	v_min_u32_e32 v2, 0xff, v2
	v_cndmask_b32_e64 v2, v2, v226, s[72:73]
	v_lshl_add_u32 v2, v2, 2, s6
	ds_add_u32 v2, v223
	v_max_i32_e32 v2, 0xffffff80, v3
	v_add_f32_e32 v3, v33, v33
	v_floor_f32_e32 v3, v3
	v_add_u32_e32 v2, 0x80, v2
	v_cvt_i32_f32_e32 v3, v3
	v_min_u32_e32 v2, 0xff, v2
	v_cndmask_b32_e64 v2, v2, v226, s[76:77]
	v_lshl_add_u32 v2, v2, 2, s6
	ds_add_u32 v2, v223
	v_max_i32_e32 v2, 0xffffff80, v3
	v_add_f32_e32 v3, v34, v34
	v_floor_f32_e32 v3, v3
	v_add_u32_e32 v2, 0x80, v2
	v_cvt_i32_f32_e32 v3, v3
	v_min_u32_e32 v2, 0xff, v2
	v_cndmask_b32_e64 v2, v2, v226, s[78:79]
	v_lshl_add_u32 v2, v2, 2, s6
	ds_add_u32 v2, v223
	v_max_i32_e32 v2, 0xffffff80, v3
	v_add_f32_e32 v3, v35, v35
	v_floor_f32_e32 v3, v3
	v_add_u32_e32 v2, 0x80, v2
	v_cvt_i32_f32_e32 v3, v3
	v_min_u32_e32 v2, 0xff, v2
	v_cndmask_b32_e64 v2, v2, v226, s[84:85]
	v_lshl_add_u32 v2, v2, 2, s6
	ds_add_u32 v2, v223
	v_max_i32_e32 v2, 0xffffff80, v3
	v_add_f32_e32 v3, v36, v36
	v_floor_f32_e32 v3, v3
	v_add_u32_e32 v2, 0x80, v2
	v_cvt_i32_f32_e32 v3, v3
	v_min_u32_e32 v2, 0xff, v2
	v_cndmask_b32_e64 v2, v2, v226, s[90:91]
	v_lshl_add_u32 v2, v2, 2, s6
	ds_add_u32 v2, v223
	v_max_i32_e32 v2, 0xffffff80, v3
	v_add_f32_e32 v3, v37, v37
	v_floor_f32_e32 v3, v3
	v_add_u32_e32 v2, 0x80, v2
	v_cvt_i32_f32_e32 v3, v3
	v_min_u32_e32 v2, 0xff, v2
	v_cndmask_b32_e64 v2, v2, v226, s[92:93]
	v_lshl_add_u32 v2, v2, 2, s6
	ds_add_u32 v2, v223
	v_max_i32_e32 v2, 0xffffff80, v3
	v_add_f32_e32 v3, v42, v42
	v_floor_f32_e32 v3, v3
	v_add_u32_e32 v2, 0x80, v2
	v_cvt_i32_f32_e32 v3, v3
	v_min_u32_e32 v2, 0xff, v2
	v_cndmask_b32_e64 v2, v2, v226, s[8:9]
	v_lshl_add_u32 v2, v2, 2, s6
	ds_add_u32 v2, v223
	v_max_i32_e32 v2, 0xffffff80, v3
	v_add_f32_e32 v3, v43, v43
	v_floor_f32_e32 v3, v3
	v_add_u32_e32 v2, 0x80, v2
	v_cvt_i32_f32_e32 v3, v3
	v_readlane_b32 s0, v254, 33
	v_min_u32_e32 v2, 0xff, v2
	v_readlane_b32 s1, v254, 34
	s_nop 1
	v_cndmask_b32_e64 v2, v2, v226, s[0:1]
	v_lshl_add_u32 v2, v2, 2, s6
	ds_add_u32 v2, v223
	v_max_i32_e32 v2, 0xffffff80, v3
	v_add_f32_e32 v3, v44, v44
	v_floor_f32_e32 v3, v3
	v_add_u32_e32 v2, 0x80, v2
	v_cvt_i32_f32_e32 v3, v3
	v_readlane_b32 s0, v254, 35
	v_min_u32_e32 v2, 0xff, v2
	v_readlane_b32 s1, v254, 36
	s_nop 1
	v_cndmask_b32_e64 v2, v2, v226, s[0:1]
	v_lshl_add_u32 v2, v2, 2, s6
	ds_add_u32 v2, v223
	v_max_i32_e32 v2, 0xffffff80, v3
	v_add_u32_e32 v2, 0x80, v2
	v_readlane_b32 s0, v254, 37
	v_min_u32_e32 v2, 0xff, v2
	v_readlane_b32 s1, v254, 38
	s_nop 1
	v_cndmask_b32_e64 v2, v2, v226, s[0:1]
	v_lshl_add_u32 v2, v2, 2, s6
	ds_add_u32 v2, v223
	s_waitcnt lgkmcnt(0)
	ds_read_b128 v[2:5], v7
	v_readlane_b32 s0, v254, 41
	v_readlane_b32 s1, v254, 42
	s_waitcnt lgkmcnt(0)
	v_add_u32_e32 v46, v2, v3
	v_add3_u32 v47, v46, v4, v5
	v_mov_b32_e32 v46, v47
	s_nop 1
	v_add_u32_dpp v46, v46, v46 row_shr:1 row_mask:0xf bank_mask:0xf bound_ctrl:0
	s_nop 1
	v_add_u32_dpp v46, v46, v46 row_shr:2 row_mask:0xf bank_mask:0xf bound_ctrl:0
	s_nop 1
	v_add_u32_dpp v46, v46, v46 row_shr:4 row_mask:0xf bank_mask:0xf bound_ctrl:0
	s_nop 1
	v_add_u32_dpp v46, v46, v46 row_shr:8 row_mask:0xf bank_mask:0xf bound_ctrl:0
	s_nop 1
	v_add_u32_dpp v46, v46, v46 row_bcast:15 row_mask:0xa bank_mask:0xf
	s_nop 1
	v_add_u32_dpp v46, v46, v46 row_bcast:31 row_mask:0xc bank_mask:0xf
	s_nop 1
	v_readlane_b32 s0, v46, 63
	s_nop 1
	v_sub_u32_e32 v48, s0, v46
	v_add_u32_e32 v46, v48, v47
	v_mov_b32_e32 v47, v48
	v_add_u32_e32 v50, v47, v5
	v_cmp_gt_u32_e32 vcc, s63, v50
	v_mov_b32_e32 v48, 3
	v_mov_b32_e32 v49, v47
	s_and_saveexec_b64 s[0:1], vcc
	s_cbranch_execz .LBB0_388
; __device__ __forceinline__ unsigned skey_of(float f) { const unsigned u = __float_as_uint(f); return u ^ ((unsigned)((int)u >> 31) | 0x80000000u); }
; template <int NJ>
; __device__ __forceinline__ void select_rows(const GAS float* sr0, GAS unsigned long long* mb0, LAS unsigned* hist, LAS unsigned* kbuf, int ntl, int lane) {
;     ...
;             if (c + hv.w >= 256u) { dl = 3; above = c; cnt = hv.w; } else { c += hv.w; if (c + hv.z >= 256u) { dl = 2; above = c; cnt = hv.z; } else { c += hv.z; if (c + hv.y >= 256u) { dl = 1; above = c; cnt = hv.y; } else { c += hv.y; dl = 0; above = c; cnt = hv.x; } } }
;             const unsigned long long bm = __ballot(mine);
;             const int src = bm ? (int)__builtin_ctzll(bm) : 0;
;             B = (unsigned)__builtin_amdgcn_readlane((int)(4 * lane + dl), src);
;             rem = 256u - (unsigned)__builtin_amdgcn_readlane((int)above, src);
;             C = (unsigned)__builtin_amdgcn_readlane((int)cnt, src);
;         }
;         const unsigned klo = (B == 0u) ? 1u : skey_of((float)((int)B - 128) * 0.5f);
;         const unsigned khi = (B == 255u) ? 0xffffffffu : skey_of((float)((int)B - 127) * 0.5f);
;         const unsigned range = khi - klo;
;         unsigned tau = 0u, remf = 0u, cnteq = 0u; bool generic = C > 64u;
;         if (!generic) {
; #pragma unroll
;             for (int j = 0; j < NJ; ++j) {
;                 if ((key[j] - klo) < range) { const unsigned slot = __hip_atomic_fetch_add(hist + 257, 1u, __ATOMIC_RELAXED, __HIP_MEMORY_SCOPE_WORKGROUP); hist[258 + (slot & 63u)] = key[j]; }
	v_add_u32_e32 v5, v50, v4
	v_cmp_gt_u32_e32 vcc, s63, v5
	v_mov_b32_e32 v48, 2
	s_and_saveexec_b64 s[2:3], vcc
	v_add_u32_e32 v4, v5, v3
	s_movk_i32 s4, 0xff
	v_cmp_lt_u32_e32 vcc, s4, v4
	s_nop 1
	v_cndmask_b32_e64 v48, 0, 1, vcc
	v_cndmask_b32_e32 v50, v4, v5, vcc
	v_cndmask_b32_e32 v4, v2, v3, vcc
	s_or_b64 exec, exec, s[2:3]
	v_mov_b32_e32 v5, v4
	v_mov_b32_e32 v49, v50
.LBB0_388:
	s_or_b64 exec, exec, s[0:1]
	v_ashrrev_i32_e32 v2, 31, v45
	s_brev_b32 s0, 1
	v_bitop3_b32 v2, v2, v45, s0 bitop3:0x36
	v_cndmask_b32_e64 v4, v2, 0, s[94:95]
	v_ashrrev_i32_e32 v2, 31, v10
	v_bitop3_b32 v2, v2, v10, s0 bitop3:0x36
	v_cndmask_b32_e64 v10, v2, 0, s[14:15]
	v_ashrrev_i32_e32 v2, 31, v11
	v_bitop3_b32 v2, v2, v11, s0 bitop3:0x36
	v_cndmask_b32_e64 v11, v2, 0, s[16:17]
	v_ashrrev_i32_e32 v2, 31, v12
	v_bitop3_b32 v2, v2, v12, s0 bitop3:0x36
	v_cndmask_b32_e64 v12, v2, 0, s[18:19]
	v_ashrrev_i32_e32 v2, 31, v13
	v_bitop3_b32 v2, v2, v13, s0 bitop3:0x36
	v_cndmask_b32_e64 v13, v2, 0, s[24:25]
	v_ashrrev_i32_e32 v2, 31, v14
	v_bitop3_b32 v2, v2, v14, s0 bitop3:0x36
	v_cndmask_b32_e64 v14, v2, 0, s[26:27]
	v_ashrrev_i32_e32 v2, 31, v15
	v_bitop3_b32 v2, v2, v15, s0 bitop3:0x36
	v_cndmask_b32_e64 v15, v2, 0, s[28:29]
	v_ashrrev_i32_e32 v2, 31, v16
	v_bitop3_b32 v2, v2, v16, s0 bitop3:0x36
	v_cndmask_b32_e64 v16, v2, 0, s[30:31]
	v_ashrrev_i32_e32 v2, 31, v17
	v_bitop3_b32 v2, v2, v17, s0 bitop3:0x36
	v_cndmask_b32_e64 v17, v2, 0, s[34:35]
	v_ashrrev_i32_e32 v2, 31, v18
	v_bitop3_b32 v2, v2, v18, s0 bitop3:0x36
	v_cndmask_b32_e64 v18, v2, 0, s[36:37]
	v_ashrrev_i32_e32 v2, 31, v19
	v_bitop3_b32 v2, v2, v19, s0 bitop3:0x36
	v_cndmask_b32_e64 v19, v2, 0, s[38:39]
	v_ashrrev_i32_e32 v2, 31, v20
	v_bitop3_b32 v2, v2, v20, s0 bitop3:0x36
	v_cndmask_b32_e64 v20, v2, 0, s[40:41]
	v_ashrrev_i32_e32 v2, 31, v21
	v_bitop3_b32 v2, v2, v21, s0 bitop3:0x36
	v_cndmask_b32_e64 v21, v2, 0, s[42:43]
	v_ashrrev_i32_e32 v2, 31, v22
	v_bitop3_b32 v2, v2, v22, s0 bitop3:0x36
	v_cndmask_b32_e64 v22, v2, 0, s[44:45]
	v_ashrrev_i32_e32 v2, 31, v23
	v_bitop3_b32 v2, v2, v23, s0 bitop3:0x36
	v_cndmask_b32_e64 v23, v2, 0, s[46:47]
	v_ashrrev_i32_e32 v2, 31, v24
	v_bitop3_b32 v2, v2, v24, s0 bitop3:0x36
	v_cndmask_b32_e64 v24, v2, 0, s[48:49]
	v_ashrrev_i32_e32 v2, 31, v25
	v_bitop3_b32 v2, v2, v25, s0 bitop3:0x36
	v_cndmask_b32_e64 v25, v2, 0, s[50:51]
	v_ashrrev_i32_e32 v2, 31, v26
	v_bitop3_b32 v2, v2, v26, s0 bitop3:0x36
	v_cndmask_b32_e64 v26, v2, 0, s[52:53]
	v_ashrrev_i32_e32 v2, 31, v27
	v_bitop3_b32 v2, v2, v27, s0 bitop3:0x36
	v_cndmask_b32_e64 v27, v2, 0, s[54:55]
	v_ashrrev_i32_e32 v2, 31, v28
	v_bitop3_b32 v2, v2, v28, s0 bitop3:0x36
	v_cndmask_b32_e64 v28, v2, 0, s[64:65]
	v_ashrrev_i32_e32 v2, 31, v29
	v_bitop3_b32 v2, v2, v29, s0 bitop3:0x36
	v_cndmask_b32_e64 v29, v2, 0, s[66:67]
	v_ashrrev_i32_e32 v2, 31, v30
	v_bitop3_b32 v2, v2, v30, s0 bitop3:0x36
	v_cndmask_b32_e64 v30, v2, 0, s[70:71]
	v_ashrrev_i32_e32 v2, 31, v31
	v_bitop3_b32 v2, v2, v31, s0 bitop3:0x36
	v_cndmask_b32_e64 v31, v2, 0, s[72:73]
	v_ashrrev_i32_e32 v2, 31, v32
	v_bitop3_b32 v2, v2, v32, s0 bitop3:0x36
	v_cndmask_b32_e64 v32, v2, 0, s[76:77]
	v_ashrrev_i32_e32 v2, 31, v33
	v_bitop3_b32 v2, v2, v33, s0 bitop3:0x36
	v_cndmask_b32_e64 v33, v2, 0, s[78:79]
	v_ashrrev_i32_e32 v2, 31, v34
	v_bitop3_b32 v2, v2, v34, s0 bitop3:0x36
	v_cndmask_b32_e64 v34, v2, 0, s[84:85]
	v_ashrrev_i32_e32 v2, 31, v35
	v_bitop3_b32 v2, v2, v35, s0 bitop3:0x36
	v_cndmask_b32_e64 v35, v2, 0, s[90:91]
	v_ashrrev_i32_e32 v2, 31, v36
	v_bitop3_b32 v2, v2, v36, s0 bitop3:0x36
	v_cndmask_b32_e64 v36, v2, 0, s[92:93]
	v_ashrrev_i32_e32 v2, 31, v37
	v_bitop3_b32 v2, v2, v37, s0 bitop3:0x36
	v_cndmask_b32_e64 v37, v2, 0, s[8:9]
	v_ashrrev_i32_e32 v2, 31, v42
	v_readlane_b32 s2, v254, 33
	v_bitop3_b32 v2, v2, v42, s0 bitop3:0x36
	v_readlane_b32 s3, v254, 34
	v_cmp_gt_u32_e32 vcc, s63, v47
	s_nop 0
	v_cndmask_b32_e64 v42, v2, 0, s[2:3]
	v_ashrrev_i32_e32 v2, 31, v43
	v_readlane_b32 s2, v254, 35
	v_bitop3_b32 v2, v2, v43, s0 bitop3:0x36
	v_readlane_b32 s3, v254, 36
	s_nop 1
	v_cndmask_b32_e64 v43, v2, 0, s[2:3]
	v_ashrrev_i32_e32 v2, 31, v44
	v_bitop3_b32 v2, v2, v44, s0 bitop3:0x36
	v_readlane_b32 s0, v254, 37
	v_readlane_b32 s1, v254, 38
	s_nop 1
	v_cndmask_b32_e64 v44, v2, 0, s[0:1]
	s_movk_i32 s0, 0xff
	v_cmp_lt_u32_e64 s[0:1], s0, v46
	s_and_b64 s[0:1], s[0:1], vcc
	s_nop 0
	v_cndmask_b32_e64 v2, 0, 1, s[0:1]
	v_cmp_ne_u32_e32 vcc, 0, v2
	s_ff1_i32_b64 s0, vcc
	s_cmp_lg_u64 vcc, 0
	s_cselect_b32 s0, s0, 0
	v_or_b32_e32 v2, v48, v6
	v_readlane_b32 s9, v5, s0
	v_readlane_b32 s2, v2, s0
	v_readlane_b32 s8, v49, s0
	s_cmp_gt_u32 s9, 64
	s_mov_b64 s[0:1], -1
	s_cbranch_scc1 .LBB0_523
	s_add_i32 s0, s2, 0xffffff80
	v_cvt_f32_i32_e32 v2, s0
	s_cmp_lg_u32 s2, 0
	s_cselect_b64 vcc, -1, 0
	s_add_i32 s0, s2, 0xffffff81
	v_mul_f32_e32 v2, 0.5, v2
	v_ashrrev_i32_e32 v3, 31, v2
	v_or_b32_e32 v3, 0x80000000, v3
	v_xor_b32_e32 v2, v3, v2
	v_cvt_f32_i32_e32 v3, s0
	s_cmpk_lg_i32 s2, 0xff
	v_cndmask_b32_e32 v2, 1, v2, vcc
	s_cselect_b64 vcc, -1, 0
	v_mul_f32_e32 v3, 0.5, v3
	v_ashrrev_i32_e32 v5, 31, v3
	v_or_b32_e32 v5, 0x80000000, v5
	v_xor_b32_e32 v3, v5, v3
	v_cndmask_b32_e32 v3, -1, v3, vcc
	v_sub_u32_e32 v3, v3, v2
	v_sub_u32_e32 v5, v4, v2
	v_cmp_lt_u32_e32 vcc, v5, v3
	s_and_saveexec_b64 s[0:1], vcc
	s_cbranch_execz .LBB0_393
	s_mov_b64 s[4:5], exec
	v_mbcnt_lo_u32_b32 v5, s4, 0
	v_mbcnt_hi_u32_b32 v5, s5, v5
	s_bcnt1_i32_b64 s4, s[4:5]
	s_mov_b32 s2, s100
	s_add_i32 s100, s100, s4
	v_add_u32_e32 v5, s2, v5
	v_and_b32_e32 v5, 63, v5
	v_lshl_add_u32 v5, v5, 2, s6
	ds_write_b32 v5, v4 offset:1032
; template <int NJ>
; __device__ __forceinline__ void select_rows(const GAS float* sr0, GAS unsigned long long* mb0, LAS unsigned* hist, LAS unsigned* kbuf, int ntl, int lane) {
;     ...
; #pragma unroll
;             for (int j = 0; j < NJ; ++j) {
;                 if ((key[j] - klo) < range) { const unsigned slot = __hip_atomic_fetch_add(hist + 257, 1u, __ATOMIC_RELAXED, __HIP_MEMORY_SCOPE_WORKGROUP); hist[258 + (slot & 63u)] = key[j]; }
;             }
.LBB0_393:
	s_or_b64 exec, exec, s[0:1]
	v_sub_u32_e32 v5, v10, v2
	v_cmp_lt_u32_e32 vcc, v5, v3
	s_and_saveexec_b64 s[0:1], vcc
	s_cbranch_execz .LBB0_397
	s_mov_b64 s[4:5], exec
	v_mbcnt_lo_u32_b32 v5, s4, 0
	v_mbcnt_hi_u32_b32 v5, s5, v5
	s_bcnt1_i32_b64 s4, s[4:5]
	s_mov_b32 s2, s100
	s_add_i32 s100, s100, s4
	v_add_u32_e32 v5, s2, v5
	v_and_b32_e32 v5, 63, v5
	v_lshl_add_u32 v5, v5, 2, s6
	ds_write_b32 v5, v10 offset:1032
.LBB0_397:
	s_or_b64 exec, exec, s[0:1]
	v_sub_u32_e32 v5, v11, v2
	v_cmp_lt_u32_e32 vcc, v5, v3
	s_and_saveexec_b64 s[0:1], vcc
	s_cbranch_execz .LBB0_401
	s_mov_b64 s[4:5], exec
	v_mbcnt_lo_u32_b32 v5, s4, 0
	v_mbcnt_hi_u32_b32 v5, s5, v5
	s_bcnt1_i32_b64 s4, s[4:5]
	s_mov_b32 s2, s100
	s_add_i32 s100, s100, s4
	v_add_u32_e32 v5, s2, v5
	v_and_b32_e32 v5, 63, v5
	v_lshl_add_u32 v5, v5, 2, s6
	ds_write_b32 v5, v11 offset:1032
.LBB0_401:
	s_or_b64 exec, exec, s[0:1]
	v_sub_u32_e32 v5, v12, v2
	v_cmp_lt_u32_e32 vcc, v5, v3
	s_and_saveexec_b64 s[0:1], vcc
	s_cbranch_execz .LBB0_405
	s_mov_b64 s[4:5], exec
	v_mbcnt_lo_u32_b32 v5, s4, 0
	v_mbcnt_hi_u32_b32 v5, s5, v5
	s_bcnt1_i32_b64 s4, s[4:5]
	s_mov_b32 s2, s100
	s_add_i32 s100, s100, s4
	v_add_u32_e32 v5, s2, v5
	v_and_b32_e32 v5, 63, v5
	v_lshl_add_u32 v5, v5, 2, s6
	ds_write_b32 v5, v12 offset:1032
.LBB0_405:
	s_or_b64 exec, exec, s[0:1]
	v_sub_u32_e32 v5, v13, v2
	v_cmp_lt_u32_e32 vcc, v5, v3
	s_and_saveexec_b64 s[0:1], vcc
	s_cbranch_execz .LBB0_409
	s_mov_b64 s[4:5], exec
	v_mbcnt_lo_u32_b32 v5, s4, 0
	v_mbcnt_hi_u32_b32 v5, s5, v5
	s_bcnt1_i32_b64 s4, s[4:5]
	s_mov_b32 s2, s100
	s_add_i32 s100, s100, s4
	v_add_u32_e32 v5, s2, v5
	v_and_b32_e32 v5, 63, v5
	v_lshl_add_u32 v5, v5, 2, s6
	ds_write_b32 v5, v13 offset:1032
.LBB0_409:
	s_or_b64 exec, exec, s[0:1]
	v_sub_u32_e32 v5, v14, v2
	v_cmp_lt_u32_e32 vcc, v5, v3
	s_and_saveexec_b64 s[0:1], vcc
	s_cbranch_execz .LBB0_413
	s_mov_b64 s[4:5], exec
	v_mbcnt_lo_u32_b32 v5, s4, 0
	v_mbcnt_hi_u32_b32 v5, s5, v5
	s_bcnt1_i32_b64 s4, s[4:5]
	s_mov_b32 s2, s100
	s_add_i32 s100, s100, s4
	v_add_u32_e32 v5, s2, v5
	v_and_b32_e32 v5, 63, v5
	v_lshl_add_u32 v5, v5, 2, s6
	ds_write_b32 v5, v14 offset:1032
.LBB0_413:
	s_or_b64 exec, exec, s[0:1]
	v_sub_u32_e32 v5, v15, v2
	v_cmp_lt_u32_e32 vcc, v5, v3
	s_and_saveexec_b64 s[0:1], vcc
	s_cbranch_execz .LBB0_417
	s_mov_b64 s[4:5], exec
	v_mbcnt_lo_u32_b32 v5, s4, 0
	v_mbcnt_hi_u32_b32 v5, s5, v5
	s_bcnt1_i32_b64 s4, s[4:5]
	s_mov_b32 s2, s100
	s_add_i32 s100, s100, s4
	v_add_u32_e32 v5, s2, v5
	v_and_b32_e32 v5, 63, v5
	v_lshl_add_u32 v5, v5, 2, s6
	ds_write_b32 v5, v15 offset:1032
.LBB0_417:
	s_or_b64 exec, exec, s[0:1]
	v_sub_u32_e32 v5, v16, v2
	v_cmp_lt_u32_e32 vcc, v5, v3
	s_and_saveexec_b64 s[0:1], vcc
	s_cbranch_execz .LBB0_421
	s_mov_b64 s[4:5], exec
	v_mbcnt_lo_u32_b32 v5, s4, 0
	v_mbcnt_hi_u32_b32 v5, s5, v5
	s_bcnt1_i32_b64 s4, s[4:5]
	s_mov_b32 s2, s100
	s_add_i32 s100, s100, s4
	v_add_u32_e32 v5, s2, v5
	v_and_b32_e32 v5, 63, v5
	v_lshl_add_u32 v5, v5, 2, s6
	ds_write_b32 v5, v16 offset:1032
.LBB0_421:
	s_or_b64 exec, exec, s[0:1]
	v_sub_u32_e32 v5, v17, v2
	v_cmp_lt_u32_e32 vcc, v5, v3
	s_and_saveexec_b64 s[0:1], vcc
	s_cbranch_execz .LBB0_425
	s_mov_b64 s[4:5], exec
	v_mbcnt_lo_u32_b32 v5, s4, 0
	v_mbcnt_hi_u32_b32 v5, s5, v5
	s_bcnt1_i32_b64 s4, s[4:5]
	s_mov_b32 s2, s100
	s_add_i32 s100, s100, s4
	v_add_u32_e32 v5, s2, v5
	v_and_b32_e32 v5, 63, v5
	v_lshl_add_u32 v5, v5, 2, s6
	ds_write_b32 v5, v17 offset:1032
.LBB0_425:
	s_or_b64 exec, exec, s[0:1]
	v_sub_u32_e32 v5, v18, v2
	v_cmp_lt_u32_e32 vcc, v5, v3
	s_and_saveexec_b64 s[0:1], vcc
	s_cbranch_execz .LBB0_429
	s_mov_b64 s[4:5], exec
	v_mbcnt_lo_u32_b32 v5, s4, 0
	v_mbcnt_hi_u32_b32 v5, s5, v5
	s_bcnt1_i32_b64 s4, s[4:5]
	s_mov_b32 s2, s100
	s_add_i32 s100, s100, s4
	v_add_u32_e32 v5, s2, v5
	v_and_b32_e32 v5, 63, v5
	v_lshl_add_u32 v5, v5, 2, s6
	ds_write_b32 v5, v18 offset:1032
.LBB0_429:
	s_or_b64 exec, exec, s[0:1]
	v_sub_u32_e32 v5, v19, v2
	v_cmp_lt_u32_e32 vcc, v5, v3
	s_and_saveexec_b64 s[0:1], vcc
	s_cbranch_execz .LBB0_433
	s_mov_b64 s[4:5], exec
	v_mbcnt_lo_u32_b32 v5, s4, 0
	v_mbcnt_hi_u32_b32 v5, s5, v5
	s_bcnt1_i32_b64 s4, s[4:5]
	s_mov_b32 s2, s100
	s_add_i32 s100, s100, s4
	v_add_u32_e32 v5, s2, v5
	v_and_b32_e32 v5, 63, v5
	v_lshl_add_u32 v5, v5, 2, s6
	ds_write_b32 v5, v19 offset:1032
.LBB0_433:
	s_or_b64 exec, exec, s[0:1]
	v_sub_u32_e32 v5, v20, v2
	v_cmp_lt_u32_e32 vcc, v5, v3
	s_and_saveexec_b64 s[0:1], vcc
	s_cbranch_execz .LBB0_437
	s_mov_b64 s[4:5], exec
	v_mbcnt_lo_u32_b32 v5, s4, 0
	v_mbcnt_hi_u32_b32 v5, s5, v5
	s_bcnt1_i32_b64 s4, s[4:5]
	s_mov_b32 s2, s100
	s_add_i32 s100, s100, s4
	v_add_u32_e32 v5, s2, v5
	v_and_b32_e32 v5, 63, v5
	v_lshl_add_u32 v5, v5, 2, s6
	ds_write_b32 v5, v20 offset:1032
.LBB0_437:
	s_or_b64 exec, exec, s[0:1]
	v_sub_u32_e32 v5, v21, v2
	v_cmp_lt_u32_e32 vcc, v5, v3
	s_and_saveexec_b64 s[0:1], vcc
	s_cbranch_execz .LBB0_441
	s_mov_b64 s[4:5], exec
	v_mbcnt_lo_u32_b32 v5, s4, 0
	v_mbcnt_hi_u32_b32 v5, s5, v5
	s_bcnt1_i32_b64 s4, s[4:5]
	s_mov_b32 s2, s100
	s_add_i32 s100, s100, s4
	v_add_u32_e32 v5, s2, v5
	v_and_b32_e32 v5, 63, v5
	v_lshl_add_u32 v5, v5, 2, s6
	ds_write_b32 v5, v21 offset:1032
.LBB0_441:
	s_or_b64 exec, exec, s[0:1]
	v_sub_u32_e32 v5, v22, v2
	v_cmp_lt_u32_e32 vcc, v5, v3
	s_and_saveexec_b64 s[0:1], vcc
	s_cbranch_execz .LBB0_445
	s_mov_b64 s[4:5], exec
	v_mbcnt_lo_u32_b32 v5, s4, 0
	v_mbcnt_hi_u32_b32 v5, s5, v5
	s_bcnt1_i32_b64 s4, s[4:5]
	s_mov_b32 s2, s100
	s_add_i32 s100, s100, s4
	v_add_u32_e32 v5, s2, v5
	v_and_b32_e32 v5, 63, v5
	v_lshl_add_u32 v5, v5, 2, s6
	ds_write_b32 v5, v22 offset:1032
; template <int NJ>
; __device__ __forceinline__ void select_rows(const GAS float* sr0, GAS unsigned long long* mb0, LAS unsigned* hist, LAS unsigned* kbuf, int ntl, int lane) {
;     ...
; #pragma unroll
;             for (int j = 0; j < NJ; ++j) {
;                 if ((key[j] - klo) < range) { const unsigned slot = __hip_atomic_fetch_add(hist + 257, 1u, __ATOMIC_RELAXED, __HIP_MEMORY_SCOPE_WORKGROUP); hist[258 + (slot & 63u)] = key[j]; }
;             }
.LBB0_445:
	s_or_b64 exec, exec, s[0:1]
	v_sub_u32_e32 v5, v23, v2
	v_cmp_lt_u32_e32 vcc, v5, v3
	s_and_saveexec_b64 s[0:1], vcc
	s_cbranch_execz .LBB0_449
	s_mov_b64 s[4:5], exec
	v_mbcnt_lo_u32_b32 v5, s4, 0
	v_mbcnt_hi_u32_b32 v5, s5, v5
	s_bcnt1_i32_b64 s4, s[4:5]
	s_mov_b32 s2, s100
	s_add_i32 s100, s100, s4
	v_add_u32_e32 v5, s2, v5
	v_and_b32_e32 v5, 63, v5
	v_lshl_add_u32 v5, v5, 2, s6
	ds_write_b32 v5, v23 offset:1032
.LBB0_449:
	s_or_b64 exec, exec, s[0:1]
	v_sub_u32_e32 v5, v24, v2
	v_cmp_lt_u32_e32 vcc, v5, v3
	s_and_saveexec_b64 s[0:1], vcc
	s_cbranch_execz .LBB0_453
	s_mov_b64 s[4:5], exec
	v_mbcnt_lo_u32_b32 v5, s4, 0
	v_mbcnt_hi_u32_b32 v5, s5, v5
	s_bcnt1_i32_b64 s4, s[4:5]
	s_mov_b32 s2, s100
	s_add_i32 s100, s100, s4
	v_add_u32_e32 v5, s2, v5
	v_and_b32_e32 v5, 63, v5
	v_lshl_add_u32 v5, v5, 2, s6
	ds_write_b32 v5, v24 offset:1032
.LBB0_453:
	s_or_b64 exec, exec, s[0:1]
	v_sub_u32_e32 v5, v25, v2
	v_cmp_lt_u32_e32 vcc, v5, v3
	s_and_saveexec_b64 s[0:1], vcc
	s_cbranch_execz .LBB0_457
	s_mov_b64 s[4:5], exec
	v_mbcnt_lo_u32_b32 v5, s4, 0
	v_mbcnt_hi_u32_b32 v5, s5, v5
	s_bcnt1_i32_b64 s4, s[4:5]
	s_mov_b32 s2, s100
	s_add_i32 s100, s100, s4
	v_add_u32_e32 v5, s2, v5
	v_and_b32_e32 v5, 63, v5
	v_lshl_add_u32 v5, v5, 2, s6
	ds_write_b32 v5, v25 offset:1032
.LBB0_457:
	s_or_b64 exec, exec, s[0:1]
	v_sub_u32_e32 v5, v26, v2
	v_cmp_lt_u32_e32 vcc, v5, v3
	s_and_saveexec_b64 s[0:1], vcc
	s_cbranch_execz .LBB0_461
	s_mov_b64 s[4:5], exec
	v_mbcnt_lo_u32_b32 v5, s4, 0
	v_mbcnt_hi_u32_b32 v5, s5, v5
	s_bcnt1_i32_b64 s4, s[4:5]
	s_mov_b32 s2, s100
	s_add_i32 s100, s100, s4
	v_add_u32_e32 v5, s2, v5
	v_and_b32_e32 v5, 63, v5
	v_lshl_add_u32 v5, v5, 2, s6
	ds_write_b32 v5, v26 offset:1032
.LBB0_461:
	s_or_b64 exec, exec, s[0:1]
	v_sub_u32_e32 v5, v27, v2
	v_cmp_lt_u32_e32 vcc, v5, v3
	s_and_saveexec_b64 s[0:1], vcc
	s_cbranch_execz .LBB0_465
	s_mov_b64 s[4:5], exec
	v_mbcnt_lo_u32_b32 v5, s4, 0
	v_mbcnt_hi_u32_b32 v5, s5, v5
	s_bcnt1_i32_b64 s4, s[4:5]
	s_mov_b32 s2, s100
	s_add_i32 s100, s100, s4
	v_add_u32_e32 v5, s2, v5
	v_and_b32_e32 v5, 63, v5
	v_lshl_add_u32 v5, v5, 2, s6
	ds_write_b32 v5, v27 offset:1032
.LBB0_465:
	s_or_b64 exec, exec, s[0:1]
	v_sub_u32_e32 v5, v28, v2
	v_cmp_lt_u32_e32 vcc, v5, v3
	s_and_saveexec_b64 s[0:1], vcc
	s_cbranch_execz .LBB0_469
	s_mov_b64 s[4:5], exec
	v_mbcnt_lo_u32_b32 v5, s4, 0
	v_mbcnt_hi_u32_b32 v5, s5, v5
	s_bcnt1_i32_b64 s4, s[4:5]
	s_mov_b32 s2, s100
	s_add_i32 s100, s100, s4
	v_add_u32_e32 v5, s2, v5
	v_and_b32_e32 v5, 63, v5
	v_lshl_add_u32 v5, v5, 2, s6
	ds_write_b32 v5, v28 offset:1032
.LBB0_469:
	s_or_b64 exec, exec, s[0:1]
	v_sub_u32_e32 v5, v29, v2
	v_cmp_lt_u32_e32 vcc, v5, v3
	s_and_saveexec_b64 s[0:1], vcc
	s_cbranch_execz .LBB0_473
	s_mov_b64 s[4:5], exec
	v_mbcnt_lo_u32_b32 v5, s4, 0
	v_mbcnt_hi_u32_b32 v5, s5, v5
	s_bcnt1_i32_b64 s4, s[4:5]
	s_mov_b32 s2, s100
	s_add_i32 s100, s100, s4
	v_add_u32_e32 v5, s2, v5
	v_and_b32_e32 v5, 63, v5
	v_lshl_add_u32 v5, v5, 2, s6
	ds_write_b32 v5, v29 offset:1032
.LBB0_473:
	s_or_b64 exec, exec, s[0:1]
	v_sub_u32_e32 v5, v30, v2
	v_cmp_lt_u32_e32 vcc, v5, v3
	s_and_saveexec_b64 s[0:1], vcc
	s_cbranch_execz .LBB0_477
	s_mov_b64 s[4:5], exec
	v_mbcnt_lo_u32_b32 v5, s4, 0
	v_mbcnt_hi_u32_b32 v5, s5, v5
	s_bcnt1_i32_b64 s4, s[4:5]
	s_mov_b32 s2, s100
	s_add_i32 s100, s100, s4
	v_add_u32_e32 v5, s2, v5
	v_and_b32_e32 v5, 63, v5
	v_lshl_add_u32 v5, v5, 2, s6
	ds_write_b32 v5, v30 offset:1032
.LBB0_477:
	s_or_b64 exec, exec, s[0:1]
	v_sub_u32_e32 v5, v31, v2
	v_cmp_lt_u32_e32 vcc, v5, v3
	s_and_saveexec_b64 s[0:1], vcc
	s_cbranch_execz .LBB0_481
	s_mov_b64 s[4:5], exec
	v_mbcnt_lo_u32_b32 v5, s4, 0
	v_mbcnt_hi_u32_b32 v5, s5, v5
	s_bcnt1_i32_b64 s4, s[4:5]
	s_mov_b32 s2, s100
	s_add_i32 s100, s100, s4
	v_add_u32_e32 v5, s2, v5
	v_and_b32_e32 v5, 63, v5
	v_lshl_add_u32 v5, v5, 2, s6
	ds_write_b32 v5, v31 offset:1032
; template <int NJ>
; __device__ __forceinline__ void select_rows(const GAS float* sr0, GAS unsigned long long* mb0, LAS unsigned* hist, LAS unsigned* kbuf, int ntl, int lane) {
;     ...
; #pragma unroll
;             for (int j = 0; j < NJ; ++j) {
;                 if ((key[j] - klo) < range) { const unsigned slot = __hip_atomic_fetch_add(hist + 257, 1u, __ATOMIC_RELAXED, __HIP_MEMORY_SCOPE_WORKGROUP); hist[258 + (slot & 63u)] = key[j]; }
;             }
.LBB0_481:
	s_or_b64 exec, exec, s[0:1]
	v_sub_u32_e32 v5, v32, v2
	v_cmp_lt_u32_e32 vcc, v5, v3
	s_and_saveexec_b64 s[0:1], vcc
	s_cbranch_execz .LBB0_485
	s_mov_b64 s[4:5], exec
	v_mbcnt_lo_u32_b32 v5, s4, 0
	v_mbcnt_hi_u32_b32 v5, s5, v5
	s_bcnt1_i32_b64 s4, s[4:5]
	s_mov_b32 s2, s100
	s_add_i32 s100, s100, s4
	v_add_u32_e32 v5, s2, v5
	v_and_b32_e32 v5, 63, v5
	v_lshl_add_u32 v5, v5, 2, s6
	ds_write_b32 v5, v32 offset:1032
.LBB0_485:
	s_or_b64 exec, exec, s[0:1]
	v_sub_u32_e32 v5, v33, v2
	v_cmp_lt_u32_e32 vcc, v5, v3
	s_and_saveexec_b64 s[0:1], vcc
	s_cbranch_execz .LBB0_489
	s_mov_b64 s[4:5], exec
	v_mbcnt_lo_u32_b32 v5, s4, 0
	v_mbcnt_hi_u32_b32 v5, s5, v5
	s_bcnt1_i32_b64 s4, s[4:5]
	s_mov_b32 s2, s100
	s_add_i32 s100, s100, s4
	v_add_u32_e32 v5, s2, v5
	v_and_b32_e32 v5, 63, v5
	v_lshl_add_u32 v5, v5, 2, s6
	ds_write_b32 v5, v33 offset:1032
.LBB0_489:
	s_or_b64 exec, exec, s[0:1]
	v_sub_u32_e32 v5, v34, v2
	v_cmp_lt_u32_e32 vcc, v5, v3
	s_and_saveexec_b64 s[0:1], vcc
	s_cbranch_execz .LBB0_493
	s_mov_b64 s[4:5], exec
	v_mbcnt_lo_u32_b32 v5, s4, 0
	v_mbcnt_hi_u32_b32 v5, s5, v5
	s_bcnt1_i32_b64 s4, s[4:5]
	s_mov_b32 s2, s100
	s_add_i32 s100, s100, s4
	v_add_u32_e32 v5, s2, v5
	v_and_b32_e32 v5, 63, v5
	v_lshl_add_u32 v5, v5, 2, s6
	ds_write_b32 v5, v34 offset:1032
.LBB0_493:
	s_or_b64 exec, exec, s[0:1]
	v_sub_u32_e32 v5, v35, v2
	v_cmp_lt_u32_e32 vcc, v5, v3
	s_and_saveexec_b64 s[0:1], vcc
	s_cbranch_execz .LBB0_497
	s_mov_b64 s[4:5], exec
	v_mbcnt_lo_u32_b32 v5, s4, 0
	v_mbcnt_hi_u32_b32 v5, s5, v5
	s_bcnt1_i32_b64 s4, s[4:5]
	s_mov_b32 s2, s100
	s_add_i32 s100, s100, s4
	v_add_u32_e32 v5, s2, v5
	v_and_b32_e32 v5, 63, v5
	v_lshl_add_u32 v5, v5, 2, s6
	ds_write_b32 v5, v35 offset:1032
.LBB0_497:
	s_or_b64 exec, exec, s[0:1]
	v_sub_u32_e32 v5, v36, v2
	v_cmp_lt_u32_e32 vcc, v5, v3
	s_and_saveexec_b64 s[0:1], vcc
	s_cbranch_execz .LBB0_501
	s_mov_b64 s[4:5], exec
	v_mbcnt_lo_u32_b32 v5, s4, 0
	v_mbcnt_hi_u32_b32 v5, s5, v5
	s_bcnt1_i32_b64 s4, s[4:5]
	s_mov_b32 s2, s100
	s_add_i32 s100, s100, s4
	v_add_u32_e32 v5, s2, v5
	v_and_b32_e32 v5, 63, v5
	v_lshl_add_u32 v5, v5, 2, s6
	ds_write_b32 v5, v36 offset:1032
.LBB0_501:
	s_or_b64 exec, exec, s[0:1]
	v_sub_u32_e32 v5, v37, v2
	v_cmp_lt_u32_e32 vcc, v5, v3
	s_and_saveexec_b64 s[0:1], vcc
	s_cbranch_execz .LBB0_505
	s_mov_b64 s[4:5], exec
	v_mbcnt_lo_u32_b32 v5, s4, 0
	v_mbcnt_hi_u32_b32 v5, s5, v5
	s_bcnt1_i32_b64 s4, s[4:5]
	s_mov_b32 s2, s100
	s_add_i32 s100, s100, s4
	v_add_u32_e32 v5, s2, v5
	v_and_b32_e32 v5, 63, v5
	v_lshl_add_u32 v5, v5, 2, s6
	ds_write_b32 v5, v37 offset:1032
.LBB0_505:
	s_or_b64 exec, exec, s[0:1]
	v_sub_u32_e32 v5, v42, v2
	v_cmp_lt_u32_e32 vcc, v5, v3
	s_and_saveexec_b64 s[0:1], vcc
	s_cbranch_execz .LBB0_509
	s_mov_b64 s[4:5], exec
	v_mbcnt_lo_u32_b32 v5, s4, 0
	v_mbcnt_hi_u32_b32 v5, s5, v5
	s_bcnt1_i32_b64 s4, s[4:5]
	s_mov_b32 s2, s100
	s_add_i32 s100, s100, s4
	v_add_u32_e32 v5, s2, v5
	v_and_b32_e32 v5, 63, v5
	v_lshl_add_u32 v5, v5, 2, s6
	ds_write_b32 v5, v42 offset:1032
.LBB0_509:
	s_or_b64 exec, exec, s[0:1]
	v_sub_u32_e32 v5, v43, v2
	v_cmp_lt_u32_e32 vcc, v5, v3
	s_and_saveexec_b64 s[0:1], vcc
	s_cbranch_execz .LBB0_513
	s_mov_b64 s[4:5], exec
	v_mbcnt_lo_u32_b32 v5, s4, 0
	v_mbcnt_hi_u32_b32 v5, s5, v5
	s_bcnt1_i32_b64 s4, s[4:5]
	s_mov_b32 s2, s100
	s_add_i32 s100, s100, s4
	v_add_u32_e32 v5, s2, v5
	v_and_b32_e32 v5, 63, v5
	v_lshl_add_u32 v5, v5, 2, s6
	ds_write_b32 v5, v43 offset:1032
.LBB0_513:
	s_or_b64 exec, exec, s[0:1]
	v_sub_u32_e32 v2, v44, v2
	v_cmp_lt_u32_e32 vcc, v2, v3
	s_and_saveexec_b64 s[0:1], vcc
	s_cbranch_execz .LBB0_517
	s_mov_b64 s[4:5], exec
	v_mbcnt_lo_u32_b32 v2, s4, 0
	v_mbcnt_hi_u32_b32 v2, s5, v2
	s_bcnt1_i32_b64 s4, s[4:5]
	s_mov_b32 s2, s100
	s_add_i32 s100, s100, s4
	v_add_u32_e32 v2, s2, v2
	v_and_b32_e32 v2, 63, v2
	v_lshl_add_u32 v2, v2, 2, s6
	ds_write_b32 v2, v44 offset:1032

; #define LAS __attribute__((address_space(3)))
; #define GAS __attribute__((address_space(1)))
; __device__ __forceinline__ unsigned skey_of(float f) { const unsigned u = __float_as_uint(f); return u ^ ((unsigned)((int)u >> 31) | 0x80000000u); }
; template <int NJ>
; __device__ __forceinline__ void select_rows(const GAS float* sr0, GAS unsigned long long* mb0, LAS unsigned* hist, LAS unsigned* kbuf, int ntl, int lane) {
;     ...
;     for (int rr = 0; rr < 8; ++rr) {
;         const GAS float* srow = sr0 + (size_t)rr * SEQ;
;         float fv[NJ];
; #pragma unroll
;         for (int j = 0; j < NJ; ++j) fv[j] = srow[64 * j];
;         { unsigned z = 0u; asm volatile("" : "+v"(z));
;           *(LAS u32x4*)(hist + 4 * lane) = (u32x4){z, z, z, z}; if (lane < 2) hist[256 + lane] = z; }
;         __builtin_amdgcn_wave_barrier();
;         unsigned key[NJ];
; #pragma unroll
;         for (int j = 0; j < NJ; ++j) {
;             const float f = fv[j]; const bool ok = (vm >> j) & 1u;
;             key[j] = ok ? skey_of(f) : 0u;
;             const int bk = min(max((int)floorf(f + f) + 128, 0), 255);
;             __hip_atomic_fetch_add(hist + (ok ? bk : 256), 1u, __ATOMIC_RELAXED, __HIP_MEMORY_SCOPE_WORKGROUP);
.LBB0_533:
	s_mov_b32 s100, 0
	s_lshl_b32 s88, s7, 11
	v_lshl_add_u64 v[2:3], s[88:89], 2, v[8:9]
	global_load_dword v33, v[2:3], off
	global_load_dword v10, v[2:3], off offset:256
	global_load_dword v11, v[2:3], off offset:512
	global_load_dword v12, v[2:3], off offset:768
	global_load_dword v13, v[2:3], off offset:1024
	global_load_dword v14, v[2:3], off offset:1280
	global_load_dword v15, v[2:3], off offset:1536
	global_load_dword v16, v[2:3], off offset:1792
	global_load_dword v17, v[2:3], off offset:2048
	global_load_dword v18, v[2:3], off offset:2304
	global_load_dword v19, v[2:3], off offset:2560
	global_load_dword v20, v[2:3], off offset:2816
	global_load_dword v21, v[2:3], off offset:3072
	global_load_dword v22, v[2:3], off offset:3328
	global_load_dword v23, v[2:3], off offset:3584
	global_load_dword v24, v[2:3], off offset:3840
	s_movk_i32 s0, 0x1000
	v_add_co_u32_e32 v2, vcc, s0, v2
	s_nop 1
	v_addc_co_u32_e32 v3, vcc, 0, v3, vcc
	global_load_dword v25, v[2:3], off
	global_load_dword v26, v[2:3], off offset:256
	global_load_dword v27, v[2:3], off offset:512
	global_load_dword v28, v[2:3], off offset:768
	global_load_dword v29, v[2:3], off offset:1024
	global_load_dword v30, v[2:3], off offset:1280
	global_load_dword v31, v[2:3], off offset:1536
	global_load_dword v32, v[2:3], off offset:1792
	v_mov_b32_e32 v2, 0
	s_nop 0
	v_mov_b32_e32 v3, v2
	v_mov_b32_e32 v4, v2
	v_mov_b32_e32 v5, v2
	ds_write_b128 v7, v[2:5]
	s_and_saveexec_b64 s[0:1], s[74:75]
	v_add_u32_e32 v3, v7, v38
	ds_write_b32 v3, v2 offset:1024
	s_or_b64 exec, exec, s[0:1]
	s_waitcnt vmcnt(23)
	v_add_f32_e32 v2, v33, v33
	v_floor_f32_e32 v2, v2
	v_cvt_i32_f32_e32 v2, v2
	s_waitcnt vmcnt(22)
	v_add_f32_e32 v3, v10, v10
	v_floor_f32_e32 v3, v3
	v_cvt_i32_f32_e32 v3, v3
	v_max_i32_e32 v2, 0xffffff80, v2
	v_add_u32_e32 v2, 0x80, v2
	v_min_u32_e32 v2, 0xff, v2
	v_cndmask_b32_e64 v2, v2, v226, s[14:15]
	v_lshl_add_u32 v2, v2, 2, s6
	ds_add_u32 v2, v223
	v_max_i32_e32 v2, 0xffffff80, v3
	s_waitcnt vmcnt(21)
	v_add_f32_e32 v3, v11, v11
	v_floor_f32_e32 v3, v3
	v_add_u32_e32 v2, 0x80, v2
	v_cvt_i32_f32_e32 v3, v3
	v_min_u32_e32 v2, 0xff, v2
	v_cndmask_b32_e64 v2, v2, v226, s[16:17]
	v_lshl_add_u32 v2, v2, 2, s6
	ds_add_u32 v2, v223
	v_max_i32_e32 v2, 0xffffff80, v3
	s_waitcnt vmcnt(20)
	v_add_f32_e32 v3, v12, v12
	v_floor_f32_e32 v3, v3
	v_add_u32_e32 v2, 0x80, v2
	v_cvt_i32_f32_e32 v3, v3
	v_min_u32_e32 v2, 0xff, v2
	v_cndmask_b32_e64 v2, v2, v226, s[18:19]
	v_lshl_add_u32 v2, v2, 2, s6
	ds_add_u32 v2, v223
	v_max_i32_e32 v2, 0xffffff80, v3
	s_waitcnt vmcnt(19)
	v_add_f32_e32 v3, v13, v13
	v_floor_f32_e32 v3, v3
	v_add_u32_e32 v2, 0x80, v2
	v_cvt_i32_f32_e32 v3, v3
	v_min_u32_e32 v2, 0xff, v2
	v_cndmask_b32_e64 v2, v2, v226, s[4:5]
	v_lshl_add_u32 v2, v2, 2, s6
	ds_add_u32 v2, v223
	v_max_i32_e32 v2, 0xffffff80, v3
	s_waitcnt vmcnt(18)
	v_add_f32_e32 v3, v14, v14
	v_floor_f32_e32 v3, v3
	v_add_u32_e32 v2, 0x80, v2
	v_cvt_i32_f32_e32 v3, v3
	v_min_u32_e32 v2, 0xff, v2
	v_cndmask_b32_e64 v2, v2, v226, s[10:11]
	v_lshl_add_u32 v2, v2, 2, s6
	ds_add_u32 v2, v223
	v_max_i32_e32 v2, 0xffffff80, v3
	s_waitcnt vmcnt(17)
	v_add_f32_e32 v3, v15, v15
	v_floor_f32_e32 v3, v3
	v_add_u32_e32 v2, 0x80, v2
	v_cvt_i32_f32_e32 v3, v3
	v_min_u32_e32 v2, 0xff, v2
	v_cndmask_b32_e64 v2, v2, v226, s[24:25]
	v_lshl_add_u32 v2, v2, 2, s6
	ds_add_u32 v2, v223
	v_max_i32_e32 v2, 0xffffff80, v3
	s_waitcnt vmcnt(16)
	v_add_f32_e32 v3, v16, v16
	v_floor_f32_e32 v3, v3
	v_add_u32_e32 v2, 0x80, v2
	v_cvt_i32_f32_e32 v3, v3
	v_min_u32_e32 v2, 0xff, v2
	v_cndmask_b32_e64 v2, v2, v226, s[26:27]
	v_lshl_add_u32 v2, v2, 2, s6
	ds_add_u32 v2, v223
	v_max_i32_e32 v2, 0xffffff80, v3
	s_waitcnt vmcnt(15)
	v_add_f32_e32 v3, v17, v17
	v_floor_f32_e32 v3, v3
	v_add_u32_e32 v2, 0x80, v2
	v_cvt_i32_f32_e32 v3, v3
	v_min_u32_e32 v2, 0xff, v2
	v_cndmask_b32_e64 v2, v2, v226, s[28:29]
	v_lshl_add_u32 v2, v2, 2, s6
	ds_add_u32 v2, v223
	v_max_i32_e32 v2, 0xffffff80, v3
	s_waitcnt vmcnt(14)
	v_add_f32_e32 v3, v18, v18
	v_floor_f32_e32 v3, v3
	v_add_u32_e32 v2, 0x80, v2
	v_cvt_i32_f32_e32 v3, v3
	v_min_u32_e32 v2, 0xff, v2
	v_cndmask_b32_e64 v2, v2, v226, s[30:31]
	v_lshl_add_u32 v2, v2, 2, s6
	ds_add_u32 v2, v223
	v_max_i32_e32 v2, 0xffffff80, v3
	s_waitcnt vmcnt(13)
	v_add_f32_e32 v3, v19, v19
	v_floor_f32_e32 v3, v3
	v_add_u32_e32 v2, 0x80, v2
	v_cvt_i32_f32_e32 v3, v3
	v_min_u32_e32 v2, 0xff, v2
	v_cndmask_b32_e64 v2, v2, v226, s[34:35]
	v_lshl_add_u32 v2, v2, 2, s6
	ds_add_u32 v2, v223
	v_max_i32_e32 v2, 0xffffff80, v3
	s_waitcnt vmcnt(12)
	v_add_f32_e32 v3, v20, v20
	v_floor_f32_e32 v3, v3
	v_add_u32_e32 v2, 0x80, v2
	v_cvt_i32_f32_e32 v3, v3
	v_min_u32_e32 v2, 0xff, v2
	v_cndmask_b32_e64 v2, v2, v226, s[36:37]
	v_lshl_add_u32 v2, v2, 2, s6
	ds_add_u32 v2, v223
	v_max_i32_e32 v2, 0xffffff80, v3
	s_waitcnt vmcnt(11)
	v_add_f32_e32 v3, v21, v21
	v_floor_f32_e32 v3, v3
	v_add_u32_e32 v2, 0x80, v2
	v_cvt_i32_f32_e32 v3, v3
	v_min_u32_e32 v2, 0xff, v2
	v_cndmask_b32_e64 v2, v2, v226, s[38:39]
	v_lshl_add_u32 v2, v2, 2, s6
	ds_add_u32 v2, v223
	v_max_i32_e32 v2, 0xffffff80, v3
	s_waitcnt vmcnt(10)
	v_add_f32_e32 v3, v22, v22
	v_floor_f32_e32 v3, v3
	v_add_u32_e32 v2, 0x80, v2
	v_cvt_i32_f32_e32 v3, v3
	v_min_u32_e32 v2, 0xff, v2
	v_cndmask_b32_e64 v2, v2, v226, s[40:41]
	v_lshl_add_u32 v2, v2, 2, s6
	ds_add_u32 v2, v223
	v_max_i32_e32 v2, 0xffffff80, v3
	s_waitcnt vmcnt(9)
	v_add_f32_e32 v3, v23, v23
	v_floor_f32_e32 v3, v3
	v_add_u32_e32 v2, 0x80, v2
	v_cvt_i32_f32_e32 v3, v3
	v_min_u32_e32 v2, 0xff, v2
	v_cndmask_b32_e64 v2, v2, v226, s[42:43]
	v_lshl_add_u32 v2, v2, 2, s6
	ds_add_u32 v2, v223
	v_max_i32_e32 v2, 0xffffff80, v3
	s_waitcnt vmcnt(8)
; #define LAS __attribute__((address_space(3)))
; __device__ __forceinline__ unsigned skey_of(float f) { const unsigned u = __float_as_uint(f); return u ^ ((unsigned)((int)u >> 31) | 0x80000000u); }
; template <int NJ>
; __device__ __forceinline__ void select_rows(const GAS float* sr0, GAS unsigned long long* mb0, LAS unsigned* hist, LAS unsigned* kbuf, int ntl, int lane) {
;     ...
; #pragma unroll
;         for (int j = 0; j < NJ; ++j) {
;             const float f = fv[j]; const bool ok = (vm >> j) & 1u;
;             key[j] = ok ? skey_of(f) : 0u;
;             const int bk = min(max((int)floorf(f + f) + 128, 0), 255);
;             __hip_atomic_fetch_add(hist + (ok ? bk : 256), 1u, __ATOMIC_RELAXED, __HIP_MEMORY_SCOPE_WORKGROUP);
;         }
;         __builtin_amdgcn_wave_barrier();
;         asm volatile("s_waitcnt lgkmcnt(0)" ::: "memory");
;         unsigned B, rem, C;
;         {
;             const u32x4 hv = *(const LAS u32x4*)(hist + 4 * lane);
;             const unsigned s4 = hv.x + hv.y + hv.z + hv.w;
;             unsigned S = s4;
; #pragma unroll
;             for (int off = 1; off < 64; off <<= 1) { const unsigned n = __shfl_down(S, off); if (lane + off < 64) S += n; }
;             const unsigned excl = S - s4;
;             const bool mine = (excl < 256u) && (256u <= S);
;             unsigned dl, above, cnt, c = excl;
;             if (c + hv.w >= 256u) { dl = 3; above = c; cnt = hv.w; } else { c += hv.w; if (c + hv.z >= 256u) { dl = 2; above = c; cnt = hv.z; } else { c += hv.z; if (c + hv.y >= 256u) { dl = 1; above = c; cnt = hv.y; } else { c += hv.y; dl = 0; above = c; cnt = hv.x; } } }
	v_add_f32_e32 v3, v24, v24
	v_floor_f32_e32 v3, v3
	v_add_u32_e32 v2, 0x80, v2
	v_cvt_i32_f32_e32 v3, v3
	v_min_u32_e32 v2, 0xff, v2
	v_cndmask_b32_e64 v2, v2, v226, s[44:45]
	v_lshl_add_u32 v2, v2, 2, s6
	ds_add_u32 v2, v223
	v_max_i32_e32 v2, 0xffffff80, v3
	s_waitcnt vmcnt(7)
	v_add_f32_e32 v3, v25, v25
	v_floor_f32_e32 v3, v3
	v_add_u32_e32 v2, 0x80, v2
	v_cvt_i32_f32_e32 v3, v3
	v_min_u32_e32 v2, 0xff, v2
	v_cndmask_b32_e64 v2, v2, v226, s[46:47]
	v_lshl_add_u32 v2, v2, 2, s6
	ds_add_u32 v2, v223
	v_max_i32_e32 v2, 0xffffff80, v3
	s_waitcnt vmcnt(6)
	v_add_f32_e32 v3, v26, v26
	v_floor_f32_e32 v3, v3
	v_add_u32_e32 v2, 0x80, v2
	v_cvt_i32_f32_e32 v3, v3
	v_min_u32_e32 v2, 0xff, v2
	v_cndmask_b32_e64 v2, v2, v226, s[48:49]
	v_lshl_add_u32 v2, v2, 2, s6
	ds_add_u32 v2, v223
	v_max_i32_e32 v2, 0xffffff80, v3
	s_waitcnt vmcnt(5)
	v_add_f32_e32 v3, v27, v27
	v_floor_f32_e32 v3, v3
	v_add_u32_e32 v2, 0x80, v2
	v_cvt_i32_f32_e32 v3, v3
	v_min_u32_e32 v2, 0xff, v2
	v_cndmask_b32_e64 v2, v2, v226, s[50:51]
	v_lshl_add_u32 v2, v2, 2, s6
	ds_add_u32 v2, v223
	v_max_i32_e32 v2, 0xffffff80, v3
	s_waitcnt vmcnt(4)
	v_add_f32_e32 v3, v28, v28
	v_floor_f32_e32 v3, v3
	v_add_u32_e32 v2, 0x80, v2
	v_cvt_i32_f32_e32 v3, v3
	v_min_u32_e32 v2, 0xff, v2
	v_cndmask_b32_e64 v2, v2, v226, s[52:53]
	v_lshl_add_u32 v2, v2, 2, s6
	ds_add_u32 v2, v223
	v_max_i32_e32 v2, 0xffffff80, v3
	s_waitcnt vmcnt(3)
	v_add_f32_e32 v3, v29, v29
	v_floor_f32_e32 v3, v3
	v_add_u32_e32 v2, 0x80, v2
	v_cvt_i32_f32_e32 v3, v3
	v_min_u32_e32 v2, 0xff, v2
	v_cndmask_b32_e64 v2, v2, v226, s[64:65]
	v_lshl_add_u32 v2, v2, 2, s6
	ds_add_u32 v2, v223
	v_max_i32_e32 v2, 0xffffff80, v3
	s_waitcnt vmcnt(2)
	v_add_f32_e32 v3, v30, v30
	v_floor_f32_e32 v3, v3
	v_add_u32_e32 v2, 0x80, v2
	v_cvt_i32_f32_e32 v3, v3
	v_min_u32_e32 v2, 0xff, v2
	v_cndmask_b32_e64 v2, v2, v226, s[66:67]
	v_lshl_add_u32 v2, v2, 2, s6
	ds_add_u32 v2, v223
	v_max_i32_e32 v2, 0xffffff80, v3
	s_waitcnt vmcnt(1)
	v_add_f32_e32 v3, v31, v31
	v_floor_f32_e32 v3, v3
	v_add_u32_e32 v2, 0x80, v2
	v_cvt_i32_f32_e32 v3, v3
	v_min_u32_e32 v2, 0xff, v2
	v_cndmask_b32_e64 v2, v2, v226, s[70:71]
	v_lshl_add_u32 v2, v2, 2, s6
	ds_add_u32 v2, v223
	v_max_i32_e32 v2, 0xffffff80, v3
	s_waitcnt vmcnt(0)
	v_add_f32_e32 v3, v32, v32
	v_floor_f32_e32 v3, v3
	v_add_u32_e32 v2, 0x80, v2
	v_cvt_i32_f32_e32 v3, v3
	v_min_u32_e32 v2, 0xff, v2
	v_cndmask_b32_e64 v2, v2, v226, s[72:73]
	v_lshl_add_u32 v2, v2, 2, s6
	ds_add_u32 v2, v223
	v_max_i32_e32 v2, 0xffffff80, v3
	v_add_u32_e32 v2, 0x80, v2
	v_min_u32_e32 v2, 0xff, v2
	v_cndmask_b32_e64 v2, v2, v226, s[76:77]
	v_lshl_add_u32 v2, v2, 2, s6
	ds_add_u32 v2, v223
	s_waitcnt lgkmcnt(0)
	ds_read_b128 v[2:5], v7
	v_readlane_b32 s0, v254, 33
	v_readlane_b32 s1, v254, 34
	s_waitcnt lgkmcnt(0)
	v_add_u32_e32 v34, v2, v3
	v_add3_u32 v35, v34, v4, v5
	v_mov_b32_e32 v34, v35
	s_nop 1
	v_add_u32_dpp v34, v34, v34 row_shr:1 row_mask:0xf bank_mask:0xf bound_ctrl:0
	s_nop 1
	v_add_u32_dpp v34, v34, v34 row_shr:2 row_mask:0xf bank_mask:0xf bound_ctrl:0
	s_nop 1
	v_add_u32_dpp v34, v34, v34 row_shr:4 row_mask:0xf bank_mask:0xf bound_ctrl:0
	s_nop 1
	v_add_u32_dpp v34, v34, v34 row_shr:8 row_mask:0xf bank_mask:0xf bound_ctrl:0
	s_nop 1
	v_add_u32_dpp v34, v34, v34 row_bcast:15 row_mask:0xa bank_mask:0xf
	s_nop 1
	v_add_u32_dpp v34, v34, v34 row_bcast:31 row_mask:0xc bank_mask:0xf
	s_nop 1
	v_readlane_b32 s0, v34, 63
	s_nop 1
	v_sub_u32_e32 v36, s0, v34
	v_add_u32_e32 v34, v36, v35
	v_mov_b32_e32 v35, v36
	v_add_u32_e32 v42, v35, v5
	v_cmp_gt_u32_e32 vcc, s63, v42
	v_mov_b32_e32 v36, 3
	v_mov_b32_e32 v37, v35
	s_and_saveexec_b64 s[0:1], vcc
	s_cbranch_execz .LBB0_539
	v_add_u32_e32 v5, v42, v4
	v_cmp_gt_u32_e32 vcc, s63, v5
	v_mov_b32_e32 v36, 2
	s_and_saveexec_b64 s[2:3], vcc
	v_add_u32_e32 v4, v5, v3
	s_movk_i32 s8, 0xff
	v_cmp_lt_u32_e32 vcc, s8, v4
	s_nop 1
	v_cndmask_b32_e64 v36, 0, 1, vcc
	v_cndmask_b32_e32 v42, v4, v5, vcc
	v_cndmask_b32_e32 v4, v2, v3, vcc
	s_or_b64 exec, exec, s[2:3]
	v_mov_b32_e32 v5, v4
	v_mov_b32_e32 v37, v42
.LBB0_539:
	s_or_b64 exec, exec, s[0:1]
	v_ashrrev_i32_e32 v2, 31, v33
	s_brev_b32 s0, 1
	v_bitop3_b32 v2, v2, v33, s0 bitop3:0x36
	v_cndmask_b32_e64 v4, v2, 0, s[14:15]
	v_ashrrev_i32_e32 v2, 31, v10
	v_bitop3_b32 v2, v2, v10, s0 bitop3:0x36
	v_cndmask_b32_e64 v10, v2, 0, s[16:17]
	v_ashrrev_i32_e32 v2, 31, v11
	v_bitop3_b32 v2, v2, v11, s0 bitop3:0x36
	v_cndmask_b32_e64 v11, v2, 0, s[18:19]
	v_ashrrev_i32_e32 v2, 31, v12
	v_bitop3_b32 v2, v2, v12, s0 bitop3:0x36
	v_cndmask_b32_e64 v12, v2, 0, s[4:5]
	v_ashrrev_i32_e32 v2, 31, v13
	v_bitop3_b32 v2, v2, v13, s0 bitop3:0x36
	v_cndmask_b32_e64 v13, v2, 0, s[10:11]
	v_ashrrev_i32_e32 v2, 31, v14
	v_bitop3_b32 v2, v2, v14, s0 bitop3:0x36
	v_cndmask_b32_e64 v14, v2, 0, s[24:25]
	v_ashrrev_i32_e32 v2, 31, v15
	v_bitop3_b32 v2, v2, v15, s0 bitop3:0x36
	v_cndmask_b32_e64 v15, v2, 0, s[26:27]
	v_ashrrev_i32_e32 v2, 31, v16
	v_bitop3_b32 v2, v2, v16, s0 bitop3:0x36
	v_cndmask_b32_e64 v16, v2, 0, s[28:29]
	v_ashrrev_i32_e32 v2, 31, v17
	v_bitop3_b32 v2, v2, v17, s0 bitop3:0x36
	v_cndmask_b32_e64 v17, v2, 0, s[30:31]
	v_ashrrev_i32_e32 v2, 31, v18
	v_bitop3_b32 v2, v2, v18, s0 bitop3:0x36
	v_cndmask_b32_e64 v18, v2, 0, s[34:35]
	v_ashrrev_i32_e32 v2, 31, v19
	v_bitop3_b32 v2, v2, v19, s0 bitop3:0x36
	v_cndmask_b32_e64 v19, v2, 0, s[36:37]
	v_ashrrev_i32_e32 v2, 31, v20
	v_bitop3_b32 v2, v2, v20, s0 bitop3:0x36
	v_cndmask_b32_e64 v20, v2, 0, s[38:39]
	v_ashrrev_i32_e32 v2, 31, v21
	v_bitop3_b32 v2, v2, v21, s0 bitop3:0x36
	v_cndmask_b32_e64 v21, v2, 0, s[40:41]
	v_ashrrev_i32_e32 v2, 31, v22
	v_bitop3_b32 v2, v2, v22, s0 bitop3:0x36
; #define LAS __attribute__((address_space(3)))
; template <int NJ>
; __device__ __forceinline__ void select_rows(const GAS float* sr0, GAS unsigned long long* mb0, LAS unsigned* hist, LAS unsigned* kbuf, int ntl, int lane) {
;     ...
;             key[j] = ok ? skey_of(f) : 0u;
;             const int bk = min(max((int)floorf(f + f) + 128, 0), 255);
;             __hip_atomic_fetch_add(hist + (ok ? bk : 256), 1u, __ATOMIC_RELAXED, __HIP_MEMORY_SCOPE_WORKGROUP);
;         }
;         __builtin_amdgcn_wave_barrier();
;         asm volatile("s_waitcnt lgkmcnt(0)" ::: "memory");
;         unsigned B, rem, C;
;         {
;             const u32x4 hv = *(const LAS u32x4*)(hist + 4 * lane);
;             const unsigned s4 = hv.x + hv.y + hv.z + hv.w;
;             unsigned S = s4;
; #pragma unroll
;             for (int off = 1; off < 64; off <<= 1) { const unsigned n = __shfl_down(S, off); if (lane + off < 64) S += n; }
;             const unsigned excl = S - s4;
;             const bool mine = (excl < 256u) && (256u <= S);
;             unsigned dl, above, cnt, c = excl;
;             if (c + hv.w >= 256u) { dl = 3; above = c; cnt = hv.w; } else { c += hv.w; if (c + hv.z >= 256u) { dl = 2; above = c; cnt = hv.z; } else { c += hv.z; if (c + hv.y >= 256u) { dl = 1; above = c; cnt = hv.y; } else { c += hv.y; dl = 0; above = c; cnt = hv.x; } } }
;             const unsigned long long bm = __ballot(mine);
;             const int src = bm ? (int)__builtin_ctzll(bm) : 0;
;             B = (unsigned)__builtin_amdgcn_readlane((int)(4 * lane + dl), src);
;             rem = 256u - (unsigned)__builtin_amdgcn_readlane((int)above, src);
;             C = (unsigned)__builtin_amdgcn_readlane((int)cnt, src);
;         }
;         const unsigned klo = (B == 0u) ? 1u : skey_of((float)((int)B - 128) * 0.5f);
;         const unsigned khi = (B == 255u) ? 0xffffffffu : skey_of((float)((int)B - 127) * 0.5f);
;         const unsigned range = khi - klo;
;         unsigned tau = 0u, remf = 0u, cnteq = 0u; bool generic = C > 64u;
;         if (!generic) {
; #pragma unroll
;             for (int j = 0; j < NJ; ++j) {
;                 if ((key[j] - klo) < range) { const unsigned slot = __hip_atomic_fetch_add(hist + 257, 1u, __ATOMIC_RELAXED, __HIP_MEMORY_SCOPE_WORKGROUP); hist[258 + (slot & 63u)] = key[j]; }
;             }
	v_cndmask_b32_e64 v22, v2, 0, s[42:43]
	v_ashrrev_i32_e32 v2, 31, v23
	v_bitop3_b32 v2, v2, v23, s0 bitop3:0x36
	v_cndmask_b32_e64 v23, v2, 0, s[44:45]
	v_ashrrev_i32_e32 v2, 31, v24
	v_bitop3_b32 v2, v2, v24, s0 bitop3:0x36
	v_cndmask_b32_e64 v24, v2, 0, s[46:47]
	v_ashrrev_i32_e32 v2, 31, v25
	v_bitop3_b32 v2, v2, v25, s0 bitop3:0x36
	v_cndmask_b32_e64 v25, v2, 0, s[48:49]
	v_ashrrev_i32_e32 v2, 31, v26
	v_bitop3_b32 v2, v2, v26, s0 bitop3:0x36
	v_cndmask_b32_e64 v26, v2, 0, s[50:51]
	v_ashrrev_i32_e32 v2, 31, v27
	v_bitop3_b32 v2, v2, v27, s0 bitop3:0x36
	v_cndmask_b32_e64 v27, v2, 0, s[52:53]
	v_ashrrev_i32_e32 v2, 31, v28
	v_bitop3_b32 v2, v2, v28, s0 bitop3:0x36
	v_cndmask_b32_e64 v28, v2, 0, s[64:65]
	v_ashrrev_i32_e32 v2, 31, v29
	v_bitop3_b32 v2, v2, v29, s0 bitop3:0x36
	v_cndmask_b32_e64 v29, v2, 0, s[66:67]
	v_ashrrev_i32_e32 v2, 31, v30
	v_bitop3_b32 v2, v2, v30, s0 bitop3:0x36
	v_cndmask_b32_e64 v30, v2, 0, s[70:71]
	v_ashrrev_i32_e32 v2, 31, v31
	v_bitop3_b32 v2, v2, v31, s0 bitop3:0x36
	v_cndmask_b32_e64 v31, v2, 0, s[72:73]
	v_ashrrev_i32_e32 v2, 31, v32
	v_bitop3_b32 v2, v2, v32, s0 bitop3:0x36
	s_movk_i32 s0, 0xff
	v_cmp_gt_u32_e32 vcc, s63, v35
	v_cmp_lt_u32_e64 s[0:1], s0, v34
	s_and_b64 s[0:1], s[0:1], vcc
	v_cndmask_b32_e64 v32, v2, 0, s[76:77]
	v_cndmask_b32_e64 v2, 0, 1, s[0:1]
	v_cmp_ne_u32_e32 vcc, 0, v2
	s_ff1_i32_b64 s0, vcc
	s_cmp_lg_u64 vcc, 0
	s_cselect_b32 s0, s0, 0
	v_or_b32_e32 v2, v36, v6
	v_readlane_b32 s55, v5, s0
	v_readlane_b32 s2, v2, s0
	v_readlane_b32 s54, v37, s0
	s_cmp_gt_u32 s55, 64
	s_mov_b64 s[0:1], -1
	s_cbranch_scc1 .LBB0_642
	s_add_i32 s0, s2, 0xffffff80
	v_cvt_f32_i32_e32 v2, s0
	s_cmp_lg_u32 s2, 0
	s_cselect_b64 vcc, -1, 0
	s_add_i32 s0, s2, 0xffffff81
	v_mul_f32_e32 v2, 0.5, v2
	v_ashrrev_i32_e32 v3, 31, v2
	v_or_b32_e32 v3, 0x80000000, v3
	v_xor_b32_e32 v2, v3, v2
	v_cvt_f32_i32_e32 v3, s0
	s_cmpk_lg_i32 s2, 0xff
	v_cndmask_b32_e32 v2, 1, v2, vcc
	s_cselect_b64 vcc, -1, 0
	v_mul_f32_e32 v3, 0.5, v3
	v_ashrrev_i32_e32 v5, 31, v3
	v_or_b32_e32 v5, 0x80000000, v5
	v_xor_b32_e32 v3, v5, v3
	v_cndmask_b32_e32 v3, -1, v3, vcc
	v_sub_u32_e32 v3, v3, v2
	v_sub_u32_e32 v5, v4, v2
	v_cmp_lt_u32_e32 vcc, v5, v3
	s_and_saveexec_b64 s[0:1], vcc
	s_cbranch_execz .LBB0_544
	s_mov_b64 s[8:9], exec
	v_mbcnt_lo_u32_b32 v5, s8, 0
	v_mbcnt_hi_u32_b32 v5, s9, v5
	s_bcnt1_i32_b64 s8, s[8:9]
	s_mov_b32 s2, s100
	s_add_i32 s100, s100, s8
	v_add_u32_e32 v5, s2, v5
	v_and_b32_e32 v5, 63, v5
	v_lshl_add_u32 v5, v5, 2, s6
	ds_write_b32 v5, v4 offset:1032
.LBB0_544:
	s_or_b64 exec, exec, s[0:1]
	v_sub_u32_e32 v5, v10, v2
	v_cmp_lt_u32_e32 vcc, v5, v3
	s_and_saveexec_b64 s[0:1], vcc
	s_cbranch_execz .LBB0_548
	s_mov_b64 s[8:9], exec
	v_mbcnt_lo_u32_b32 v5, s8, 0
	v_mbcnt_hi_u32_b32 v5, s9, v5
	s_bcnt1_i32_b64 s8, s[8:9]
	s_mov_b32 s2, s100
	s_add_i32 s100, s100, s8
	v_add_u32_e32 v5, s2, v5
	v_and_b32_e32 v5, 63, v5
	v_lshl_add_u32 v5, v5, 2, s6
	ds_write_b32 v5, v10 offset:1032
.LBB0_548:
	s_or_b64 exec, exec, s[0:1]
	v_sub_u32_e32 v5, v11, v2
	v_cmp_lt_u32_e32 vcc, v5, v3
	s_and_saveexec_b64 s[0:1], vcc
	s_cbranch_execz .LBB0_552
	s_mov_b64 s[8:9], exec
	v_mbcnt_lo_u32_b32 v5, s8, 0
	v_mbcnt_hi_u32_b32 v5, s9, v5
	s_bcnt1_i32_b64 s8, s[8:9]
	s_mov_b32 s2, s100
	s_add_i32 s100, s100, s8
	v_add_u32_e32 v5, s2, v5
	v_and_b32_e32 v5, 63, v5
	v_lshl_add_u32 v5, v5, 2, s6
	ds_write_b32 v5, v11 offset:1032
.LBB0_552:
	s_or_b64 exec, exec, s[0:1]
	v_sub_u32_e32 v5, v12, v2
	v_cmp_lt_u32_e32 vcc, v5, v3
	s_and_saveexec_b64 s[0:1], vcc
	s_cbranch_execz .LBB0_556
	s_mov_b64 s[8:9], exec
	v_mbcnt_lo_u32_b32 v5, s8, 0
	v_mbcnt_hi_u32_b32 v5, s9, v5
	s_bcnt1_i32_b64 s8, s[8:9]
	s_mov_b32 s2, s100
	s_add_i32 s100, s100, s8
	v_add_u32_e32 v5, s2, v5
	v_and_b32_e32 v5, 63, v5
	v_lshl_add_u32 v5, v5, 2, s6
	ds_write_b32 v5, v12 offset:1032
.LBB0_556:
	s_or_b64 exec, exec, s[0:1]
	v_sub_u32_e32 v5, v13, v2
	v_cmp_lt_u32_e32 vcc, v5, v3
	s_and_saveexec_b64 s[0:1], vcc
	s_cbranch_execz .LBB0_560
	s_mov_b64 s[8:9], exec
	v_mbcnt_lo_u32_b32 v5, s8, 0
	v_mbcnt_hi_u32_b32 v5, s9, v5
	s_bcnt1_i32_b64 s8, s[8:9]
	s_mov_b32 s2, s100
	s_add_i32 s100, s100, s8
	v_add_u32_e32 v5, s2, v5
	v_and_b32_e32 v5, 63, v5
	v_lshl_add_u32 v5, v5, 2, s6
	ds_write_b32 v5, v13 offset:1032
.LBB0_560:
	s_or_b64 exec, exec, s[0:1]
	v_sub_u32_e32 v5, v14, v2
	v_cmp_lt_u32_e32 vcc, v5, v3
	s_and_saveexec_b64 s[0:1], vcc
	s_cbranch_execz .LBB0_564
	s_mov_b64 s[8:9], exec
	v_mbcnt_lo_u32_b32 v5, s8, 0
	v_mbcnt_hi_u32_b32 v5, s9, v5
	s_bcnt1_i32_b64 s8, s[8:9]
	s_mov_b32 s2, s100
	s_add_i32 s100, s100, s8
	v_add_u32_e32 v5, s2, v5
	v_and_b32_e32 v5, 63, v5
	v_lshl_add_u32 v5, v5, 2, s6
	ds_write_b32 v5, v14 offset:1032
.LBB0_564:
	s_or_b64 exec, exec, s[0:1]
	v_sub_u32_e32 v5, v15, v2
	v_cmp_lt_u32_e32 vcc, v5, v3
	s_and_saveexec_b64 s[0:1], vcc
	s_cbranch_execz .LBB0_568
	s_mov_b64 s[8:9], exec
	v_mbcnt_lo_u32_b32 v5, s8, 0
	v_mbcnt_hi_u32_b32 v5, s9, v5
	s_bcnt1_i32_b64 s8, s[8:9]
	s_mov_b32 s2, s100
	s_add_i32 s100, s100, s8
	v_add_u32_e32 v5, s2, v5
	v_and_b32_e32 v5, 63, v5
	v_lshl_add_u32 v5, v5, 2, s6
	ds_write_b32 v5, v15 offset:1032
.LBB0_568:
	s_or_b64 exec, exec, s[0:1]
	v_sub_u32_e32 v5, v16, v2
	v_cmp_lt_u32_e32 vcc, v5, v3
	s_and_saveexec_b64 s[0:1], vcc
	s_cbranch_execz .LBB0_572
	s_mov_b64 s[8:9], exec
	v_mbcnt_lo_u32_b32 v5, s8, 0
	v_mbcnt_hi_u32_b32 v5, s9, v5
	s_bcnt1_i32_b64 s8, s[8:9]
	s_mov_b32 s2, s100
	s_add_i32 s100, s100, s8
	v_add_u32_e32 v5, s2, v5
	v_and_b32_e32 v5, 63, v5
	v_lshl_add_u32 v5, v5, 2, s6
	ds_write_b32 v5, v16 offset:1032
; template <int NJ>
; __device__ __forceinline__ void select_rows(const GAS float* sr0, GAS unsigned long long* mb0, LAS unsigned* hist, LAS unsigned* kbuf, int ntl, int lane) {
;     ...
;             for (int j = 0; j < NJ; ++j) {
;                 if ((key[j] - klo) < range) { const unsigned slot = __hip_atomic_fetch_add(hist + 257, 1u, __ATOMIC_RELAXED, __HIP_MEMORY_SCOPE_WORKGROUP); hist[258 + (slot & 63u)] = key[j]; }
;             }
;             __builtin_amdgcn_wave_barrier();
;             asm volatile("s_waitcnt lgkmcnt(0)" ::: "memory");
.LBB0_572:
	s_or_b64 exec, exec, s[0:1]
	v_sub_u32_e32 v5, v17, v2
	v_cmp_lt_u32_e32 vcc, v5, v3
	s_and_saveexec_b64 s[0:1], vcc
	s_cbranch_execz .LBB0_576
	s_mov_b64 s[8:9], exec
	v_mbcnt_lo_u32_b32 v5, s8, 0
	v_mbcnt_hi_u32_b32 v5, s9, v5
	s_bcnt1_i32_b64 s8, s[8:9]
	s_mov_b32 s2, s100
	s_add_i32 s100, s100, s8
	v_add_u32_e32 v5, s2, v5
	v_and_b32_e32 v5, 63, v5
	v_lshl_add_u32 v5, v5, 2, s6
	ds_write_b32 v5, v17 offset:1032
.LBB0_576:
	s_or_b64 exec, exec, s[0:1]
	v_sub_u32_e32 v5, v18, v2
	v_cmp_lt_u32_e32 vcc, v5, v3
	s_and_saveexec_b64 s[0:1], vcc
	s_cbranch_execz .LBB0_580
	s_mov_b64 s[8:9], exec
	v_mbcnt_lo_u32_b32 v5, s8, 0
	v_mbcnt_hi_u32_b32 v5, s9, v5
	s_bcnt1_i32_b64 s8, s[8:9]
	s_mov_b32 s2, s100
	s_add_i32 s100, s100, s8
	v_add_u32_e32 v5, s2, v5
	v_and_b32_e32 v5, 63, v5
	v_lshl_add_u32 v5, v5, 2, s6
	ds_write_b32 v5, v18 offset:1032
.LBB0_580:
	s_or_b64 exec, exec, s[0:1]
	v_sub_u32_e32 v5, v19, v2
	v_cmp_lt_u32_e32 vcc, v5, v3
	s_and_saveexec_b64 s[0:1], vcc
	s_cbranch_execz .LBB0_584
	s_mov_b64 s[8:9], exec
	v_mbcnt_lo_u32_b32 v5, s8, 0
	v_mbcnt_hi_u32_b32 v5, s9, v5
	s_bcnt1_i32_b64 s8, s[8:9]
	s_mov_b32 s2, s100
	s_add_i32 s100, s100, s8
	v_add_u32_e32 v5, s2, v5
	v_and_b32_e32 v5, 63, v5
	v_lshl_add_u32 v5, v5, 2, s6
	ds_write_b32 v5, v19 offset:1032
.LBB0_584:
	s_or_b64 exec, exec, s[0:1]
	v_sub_u32_e32 v5, v20, v2
	v_cmp_lt_u32_e32 vcc, v5, v3
	s_and_saveexec_b64 s[0:1], vcc
	s_cbranch_execz .LBB0_588
	s_mov_b64 s[8:9], exec
	v_mbcnt_lo_u32_b32 v5, s8, 0
	v_mbcnt_hi_u32_b32 v5, s9, v5
	s_bcnt1_i32_b64 s8, s[8:9]
	s_mov_b32 s2, s100
	s_add_i32 s100, s100, s8
	v_add_u32_e32 v5, s2, v5
	v_and_b32_e32 v5, 63, v5
	v_lshl_add_u32 v5, v5, 2, s6
	ds_write_b32 v5, v20 offset:1032
.LBB0_588:
	s_or_b64 exec, exec, s[0:1]
	v_sub_u32_e32 v5, v21, v2
	v_cmp_lt_u32_e32 vcc, v5, v3
	s_and_saveexec_b64 s[0:1], vcc
	s_cbranch_execz .LBB0_592
	s_mov_b64 s[8:9], exec
	v_mbcnt_lo_u32_b32 v5, s8, 0
	v_mbcnt_hi_u32_b32 v5, s9, v5
	s_bcnt1_i32_b64 s8, s[8:9]
	s_mov_b32 s2, s100
	s_add_i32 s100, s100, s8
	v_add_u32_e32 v5, s2, v5
	v_and_b32_e32 v5, 63, v5
	v_lshl_add_u32 v5, v5, 2, s6
	ds_write_b32 v5, v21 offset:1032
.LBB0_592:
	s_or_b64 exec, exec, s[0:1]
	v_sub_u32_e32 v5, v22, v2
	v_cmp_lt_u32_e32 vcc, v5, v3
	s_and_saveexec_b64 s[0:1], vcc
	s_cbranch_execz .LBB0_596
	s_mov_b64 s[8:9], exec
	v_mbcnt_lo_u32_b32 v5, s8, 0
	v_mbcnt_hi_u32_b32 v5, s9, v5
	s_bcnt1_i32_b64 s8, s[8:9]
	s_mov_b32 s2, s100
	s_add_i32 s100, s100, s8
	v_add_u32_e32 v5, s2, v5
	v_and_b32_e32 v5, 63, v5
	v_lshl_add_u32 v5, v5, 2, s6
	ds_write_b32 v5, v22 offset:1032
.LBB0_596:
	s_or_b64 exec, exec, s[0:1]
	v_sub_u32_e32 v5, v23, v2
	v_cmp_lt_u32_e32 vcc, v5, v3
	s_and_saveexec_b64 s[0:1], vcc
	s_cbranch_execz .LBB0_600
	s_mov_b64 s[8:9], exec
	v_mbcnt_lo_u32_b32 v5, s8, 0
	v_mbcnt_hi_u32_b32 v5, s9, v5
	s_bcnt1_i32_b64 s8, s[8:9]
	s_mov_b32 s2, s100
	s_add_i32 s100, s100, s8
	v_add_u32_e32 v5, s2, v5
	v_and_b32_e32 v5, 63, v5
	v_lshl_add_u32 v5, v5, 2, s6
	ds_write_b32 v5, v23 offset:1032
.LBB0_600:
	s_or_b64 exec, exec, s[0:1]
	v_sub_u32_e32 v5, v24, v2
	v_cmp_lt_u32_e32 vcc, v5, v3
	s_and_saveexec_b64 s[0:1], vcc
	s_cbranch_execz .LBB0_604
	s_mov_b64 s[8:9], exec
	v_mbcnt_lo_u32_b32 v5, s8, 0
	v_mbcnt_hi_u32_b32 v5, s9, v5
	s_bcnt1_i32_b64 s8, s[8:9]
	s_mov_b32 s2, s100
	s_add_i32 s100, s100, s8
	v_add_u32_e32 v5, s2, v5
	v_and_b32_e32 v5, 63, v5
	v_lshl_add_u32 v5, v5, 2, s6
	ds_write_b32 v5, v24 offset:1032
.LBB0_604:
	s_or_b64 exec, exec, s[0:1]
	v_sub_u32_e32 v5, v25, v2
	v_cmp_lt_u32_e32 vcc, v5, v3
	s_and_saveexec_b64 s[0:1], vcc
	s_cbranch_execz .LBB0_608
	s_mov_b64 s[8:9], exec
	v_mbcnt_lo_u32_b32 v5, s8, 0
	v_mbcnt_hi_u32_b32 v5, s9, v5
	s_bcnt1_i32_b64 s8, s[8:9]
	s_mov_b32 s2, s100
	s_add_i32 s100, s100, s8
	v_add_u32_e32 v5, s2, v5
	v_and_b32_e32 v5, 63, v5
	v_lshl_add_u32 v5, v5, 2, s6
	ds_write_b32 v5, v25 offset:1032
.LBB0_608:
	s_or_b64 exec, exec, s[0:1]
	v_sub_u32_e32 v5, v26, v2
	v_cmp_lt_u32_e32 vcc, v5, v3
	s_and_saveexec_b64 s[0:1], vcc
	s_cbranch_execz .LBB0_612
	s_mov_b64 s[8:9], exec
	v_mbcnt_lo_u32_b32 v5, s8, 0
	v_mbcnt_hi_u32_b32 v5, s9, v5
	s_bcnt1_i32_b64 s8, s[8:9]
	s_mov_b32 s2, s100
	s_add_i32 s100, s100, s8
	v_add_u32_e32 v5, s2, v5
	v_and_b32_e32 v5, 63, v5
	v_lshl_add_u32 v5, v5, 2, s6
	ds_write_b32 v5, v26 offset:1032
.LBB0_612:
	s_or_b64 exec, exec, s[0:1]
	v_sub_u32_e32 v5, v27, v2
	v_cmp_lt_u32_e32 vcc, v5, v3
	s_and_saveexec_b64 s[0:1], vcc
	s_cbranch_execz .LBB0_616
	s_mov_b64 s[8:9], exec
	v_mbcnt_lo_u32_b32 v5, s8, 0
	v_mbcnt_hi_u32_b32 v5, s9, v5
	s_bcnt1_i32_b64 s8, s[8:9]
	s_mov_b32 s2, s100
	s_add_i32 s100, s100, s8
	v_add_u32_e32 v5, s2, v5
	v_and_b32_e32 v5, 63, v5
	v_lshl_add_u32 v5, v5, 2, s6
	ds_write_b32 v5, v27 offset:1032
.LBB0_616:
	s_or_b64 exec, exec, s[0:1]
	v_sub_u32_e32 v5, v28, v2
	v_cmp_lt_u32_e32 vcc, v5, v3
	s_and_saveexec_b64 s[0:1], vcc
	s_cbranch_execz .LBB0_620
	s_mov_b64 s[8:9], exec
	v_mbcnt_lo_u32_b32 v5, s8, 0
	v_mbcnt_hi_u32_b32 v5, s9, v5
	s_bcnt1_i32_b64 s8, s[8:9]
	s_mov_b32 s2, s100
	s_add_i32 s100, s100, s8
	v_add_u32_e32 v5, s2, v5
	v_and_b32_e32 v5, 63, v5
	v_lshl_add_u32 v5, v5, 2, s6
	ds_write_b32 v5, v28 offset:1032
.LBB0_620:
	s_or_b64 exec, exec, s[0:1]
	v_sub_u32_e32 v5, v29, v2
	v_cmp_lt_u32_e32 vcc, v5, v3
	s_and_saveexec_b64 s[0:1], vcc
	s_cbranch_execz .LBB0_624
	s_mov_b64 s[8:9], exec
	v_mbcnt_lo_u32_b32 v5, s8, 0
	v_mbcnt_hi_u32_b32 v5, s9, v5
	s_bcnt1_i32_b64 s8, s[8:9]
	s_mov_b32 s2, s100
	s_add_i32 s100, s100, s8
	v_add_u32_e32 v5, s2, v5
	v_and_b32_e32 v5, 63, v5
	v_lshl_add_u32 v5, v5, 2, s6
	ds_write_b32 v5, v29 offset:1032
.LBB0_624:
	s_or_b64 exec, exec, s[0:1]
	v_sub_u32_e32 v5, v30, v2
	v_cmp_lt_u32_e32 vcc, v5, v3
	s_and_saveexec_b64 s[0:1], vcc
	s_cbranch_execz .LBB0_628
	s_mov_b64 s[8:9], exec
	v_mbcnt_lo_u32_b32 v5, s8, 0
	v_mbcnt_hi_u32_b32 v5, s9, v5
	s_bcnt1_i32_b64 s8, s[8:9]
	s_mov_b32 s2, s100
	s_add_i32 s100, s100, s8
	v_add_u32_e32 v5, s2, v5
	v_and_b32_e32 v5, 63, v5
	v_lshl_add_u32 v5, v5, 2, s6
	ds_write_b32 v5, v30 offset:1032
.LBB0_628:
	s_or_b64 exec, exec, s[0:1]
	v_sub_u32_e32 v5, v31, v2
	v_cmp_lt_u32_e32 vcc, v5, v3
	s_and_saveexec_b64 s[0:1], vcc
	s_cbranch_execz .LBB0_632
	s_mov_b64 s[8:9], exec
	v_mbcnt_lo_u32_b32 v5, s8, 0
	v_mbcnt_hi_u32_b32 v5, s9, v5
	s_bcnt1_i32_b64 s8, s[8:9]
	s_mov_b32 s2, s100
	s_add_i32 s100, s100, s8
	v_add_u32_e32 v5, s2, v5
	v_and_b32_e32 v5, 63, v5
	v_lshl_add_u32 v5, v5, 2, s6
	ds_write_b32 v5, v31 offset:1032
.LBB0_632:
	s_or_b64 exec, exec, s[0:1]
	v_sub_u32_e32 v2, v32, v2
	v_cmp_lt_u32_e32 vcc, v2, v3
	s_and_saveexec_b64 s[0:1], vcc
	s_cbranch_execz .LBB0_636
	s_mov_b64 s[8:9], exec
	v_mbcnt_lo_u32_b32 v2, s8, 0
	v_mbcnt_hi_u32_b32 v2, s9, v2
	s_bcnt1_i32_b64 s8, s[8:9]
	s_mov_b32 s2, s100
	s_add_i32 s100, s100, s8
	v_add_u32_e32 v2, s2, v2
	v_and_b32_e32 v2, 63, v2
	v_lshl_add_u32 v2, v2, 2, s6
	ds_write_b32 v2, v32 offset:1032

; #define LAS __attribute__((address_space(3)))
; #define GAS __attribute__((address_space(1)))
; __device__ __forceinline__ unsigned skey_of(float f) { const unsigned u = __float_as_uint(f); return u ^ ((unsigned)((int)u >> 31) | 0x80000000u); }
; template <int NJ>
; __device__ __forceinline__ void select_rows(const GAS float* sr0, GAS unsigned long long* mb0, LAS unsigned* hist, LAS unsigned* kbuf, int ntl, int lane) {
;     ...
;     for (int rr = 0; rr < 8; ++rr) {
;         const GAS float* srow = sr0 + (size_t)rr * SEQ;
;         float fv[NJ];
; #pragma unroll
;         for (int j = 0; j < NJ; ++j) fv[j] = srow[64 * j];
;         { unsigned z = 0u; asm volatile("" : "+v"(z));
;           *(LAS u32x4*)(hist + 4 * lane) = (u32x4){z, z, z, z}; if (lane < 2) hist[256 + lane] = z; }
;         __builtin_amdgcn_wave_barrier();
;         unsigned key[NJ];
; #pragma unroll
;         for (int j = 0; j < NJ; ++j) {
;             const float f = fv[j]; const bool ok = (vm >> j) & 1u;
;             key[j] = ok ? skey_of(f) : 0u;
;             const int bk = min(max((int)floorf(f + f) + 128, 0), 255);
;             __hip_atomic_fetch_add(hist + (ok ? bk : 256), 1u, __ATOMIC_RELAXED, __HIP_MEMORY_SCOPE_WORKGROUP);
;         }
;         __builtin_amdgcn_wave_barrier();
;         asm volatile("s_waitcnt lgkmcnt(0)" ::: "memory");
;         unsigned B, rem, C;
;         {
;             const u32x4 hv = *(const LAS u32x4*)(hist + 4 * lane);
;             const unsigned s4 = hv.x + hv.y + hv.z + hv.w;
;             unsigned S = s4;
; #pragma unroll
;             for (int off = 1; off < 64; off <<= 1) { const unsigned n = __shfl_down(S, off); if (lane + off < 64) S += n; }
;             const unsigned excl = S - s4;
;             const bool mine = (excl < 256u) && (256u <= S);
;             unsigned dl, above, cnt, c = excl;
;             if (c + hv.w >= 256u) { dl = 3; above = c; cnt = hv.w; } else { c += hv.w; if (c + hv.z >= 256u) { dl = 2; above = c; cnt = hv.z; } else { c += hv.z; if (c + hv.y >= 256u) { dl = 1; above = c; cnt = hv.y; } else { c += hv.y; dl = 0; above = c; cnt = hv.x; } } }
.LBB0_652:
	s_mov_b32 s100, 0
	s_lshl_b32 s88, s7, 11
	v_lshl_add_u64 v[2:3], s[88:89], 2, v[8:9]
	global_load_dword v25, v[2:3], off
	global_load_dword v10, v[2:3], off offset:256
	global_load_dword v11, v[2:3], off offset:512
	global_load_dword v12, v[2:3], off offset:768
	global_load_dword v13, v[2:3], off offset:1024
	global_load_dword v14, v[2:3], off offset:1280
	global_load_dword v15, v[2:3], off offset:1536
	global_load_dword v16, v[2:3], off offset:1792
	global_load_dword v17, v[2:3], off offset:2048
	global_load_dword v18, v[2:3], off offset:2304
	global_load_dword v19, v[2:3], off offset:2560
	global_load_dword v20, v[2:3], off offset:2816
	global_load_dword v21, v[2:3], off offset:3072
	global_load_dword v22, v[2:3], off offset:3328
	global_load_dword v23, v[2:3], off offset:3584
	global_load_dword v24, v[2:3], off offset:3840
	v_mov_b32_e32 v2, 0
	s_nop 0
	v_mov_b32_e32 v3, v2
	v_mov_b32_e32 v4, v2
	v_mov_b32_e32 v5, v2
	ds_write_b128 v7, v[2:5]
	s_mov_b64 s[8:9], exec
	v_readlane_b32 s38, v254, 15
	v_readlane_b32 s39, v254, 16
	s_and_b64 s[38:39], s[8:9], s[38:39]
	s_mov_b64 exec, s[38:39]
	v_add_u32_e32 v3, v7, v38
	ds_write_b32 v3, v2 offset:1024
	s_or_b64 exec, exec, s[8:9]
	s_waitcnt vmcnt(15)
	v_add_f32_e32 v2, v25, v25
	v_floor_f32_e32 v2, v2
	v_cvt_i32_f32_e32 v2, v2
	s_waitcnt vmcnt(14)
	v_add_f32_e32 v3, v10, v10
	v_floor_f32_e32 v3, v3
	v_cvt_i32_f32_e32 v3, v3
	v_max_i32_e32 v2, 0xffffff80, v2
	v_add_u32_e32 v2, 0x80, v2
	v_min_u32_e32 v2, 0xff, v2
	v_cndmask_b32_e64 v2, v2, v226, s[0:1]
	v_lshl_add_u32 v2, v2, 2, s6
	ds_add_u32 v2, v223
	v_max_i32_e32 v2, 0xffffff80, v3
	s_waitcnt vmcnt(13)
	v_add_f32_e32 v3, v11, v11
	v_floor_f32_e32 v3, v3
	v_add_u32_e32 v2, 0x80, v2
	v_cvt_i32_f32_e32 v3, v3
	v_min_u32_e32 v2, 0xff, v2
	v_cndmask_b32_e64 v2, v2, v226, s[2:3]
	v_lshl_add_u32 v2, v2, 2, s6
	ds_add_u32 v2, v223
	v_max_i32_e32 v2, 0xffffff80, v3
	s_waitcnt vmcnt(12)
	v_add_f32_e32 v3, v12, v12
	v_floor_f32_e32 v3, v3
	v_add_u32_e32 v2, 0x80, v2
	v_cvt_i32_f32_e32 v3, v3
	v_min_u32_e32 v2, 0xff, v2
	v_cndmask_b32_e64 v2, v2, v226, s[4:5]
	v_lshl_add_u32 v2, v2, 2, s6
	ds_add_u32 v2, v223
	v_max_i32_e32 v2, 0xffffff80, v3
	s_waitcnt vmcnt(11)
	v_add_f32_e32 v3, v13, v13
	v_floor_f32_e32 v3, v3
	v_add_u32_e32 v2, 0x80, v2
	v_cvt_i32_f32_e32 v3, v3
	v_min_u32_e32 v2, 0xff, v2
	v_cndmask_b32_e64 v2, v2, v226, s[10:11]
	v_lshl_add_u32 v2, v2, 2, s6
	ds_add_u32 v2, v223
	v_max_i32_e32 v2, 0xffffff80, v3
	s_waitcnt vmcnt(10)
	v_add_f32_e32 v3, v14, v14
	v_floor_f32_e32 v3, v3
	v_add_u32_e32 v2, 0x80, v2
	v_cvt_i32_f32_e32 v3, v3
	v_min_u32_e32 v2, 0xff, v2
	v_cndmask_b32_e64 v2, v2, v226, s[12:13]
	v_lshl_add_u32 v2, v2, 2, s6
	ds_add_u32 v2, v223
	v_max_i32_e32 v2, 0xffffff80, v3
	s_waitcnt vmcnt(9)
	v_add_f32_e32 v3, v15, v15
	v_floor_f32_e32 v3, v3
	v_add_u32_e32 v2, 0x80, v2
	v_cvt_i32_f32_e32 v3, v3
	v_min_u32_e32 v2, 0xff, v2
	v_cndmask_b32_e64 v2, v2, v226, s[14:15]
	v_lshl_add_u32 v2, v2, 2, s6
	ds_add_u32 v2, v223
	v_max_i32_e32 v2, 0xffffff80, v3
	s_waitcnt vmcnt(8)
	v_add_f32_e32 v3, v16, v16
	v_floor_f32_e32 v3, v3
	v_add_u32_e32 v2, 0x80, v2
	v_cvt_i32_f32_e32 v3, v3
	v_min_u32_e32 v2, 0xff, v2
	v_cndmask_b32_e64 v2, v2, v226, s[16:17]
	v_lshl_add_u32 v2, v2, 2, s6
	ds_add_u32 v2, v223
	v_max_i32_e32 v2, 0xffffff80, v3
	s_waitcnt vmcnt(7)
	v_add_f32_e32 v3, v17, v17
	v_floor_f32_e32 v3, v3
	v_add_u32_e32 v2, 0x80, v2
	v_cvt_i32_f32_e32 v3, v3
	v_min_u32_e32 v2, 0xff, v2
	v_cndmask_b32_e64 v2, v2, v226, s[18:19]
	v_lshl_add_u32 v2, v2, 2, s6
	ds_add_u32 v2, v223
	v_max_i32_e32 v2, 0xffffff80, v3
	s_waitcnt vmcnt(6)
	v_add_f32_e32 v3, v18, v18
	v_floor_f32_e32 v3, v3
	v_add_u32_e32 v2, 0x80, v2
	v_cvt_i32_f32_e32 v3, v3
	v_min_u32_e32 v2, 0xff, v2
	v_cndmask_b32_e64 v2, v2, v226, s[52:53]
	v_lshl_add_u32 v2, v2, 2, s6
	ds_add_u32 v2, v223
	v_max_i32_e32 v2, 0xffffff80, v3
	s_waitcnt vmcnt(5)
	v_add_f32_e32 v3, v19, v19
	v_floor_f32_e32 v3, v3
	v_add_u32_e32 v2, 0x80, v2
	v_cvt_i32_f32_e32 v3, v3
	v_min_u32_e32 v2, 0xff, v2
	v_cndmask_b32_e64 v2, v2, v226, s[54:55]
	v_lshl_add_u32 v2, v2, 2, s6
	ds_add_u32 v2, v223
	v_max_i32_e32 v2, 0xffffff80, v3
	s_waitcnt vmcnt(4)
	v_add_f32_e32 v3, v20, v20
	v_floor_f32_e32 v3, v3
	v_add_u32_e32 v2, 0x80, v2
	v_cvt_i32_f32_e32 v3, v3
	v_min_u32_e32 v2, 0xff, v2
	v_cndmask_b32_e64 v2, v2, v226, s[24:25]
	v_lshl_add_u32 v2, v2, 2, s6
	ds_add_u32 v2, v223
	v_max_i32_e32 v2, 0xffffff80, v3
	s_waitcnt vmcnt(3)
	v_add_f32_e32 v3, v21, v21
	v_floor_f32_e32 v3, v3
	v_add_u32_e32 v2, 0x80, v2
	v_cvt_i32_f32_e32 v3, v3
	v_min_u32_e32 v2, 0xff, v2
	v_cndmask_b32_e64 v2, v2, v226, s[26:27]
	v_lshl_add_u32 v2, v2, 2, s6
	ds_add_u32 v2, v223
	v_max_i32_e32 v2, 0xffffff80, v3
	s_waitcnt vmcnt(2)
	v_add_f32_e32 v3, v22, v22
	v_floor_f32_e32 v3, v3
	v_add_u32_e32 v2, 0x80, v2
	v_cvt_i32_f32_e32 v3, v3
	v_min_u32_e32 v2, 0xff, v2
	v_cndmask_b32_e64 v2, v2, v226, s[28:29]
	v_lshl_add_u32 v2, v2, 2, s6
	ds_add_u32 v2, v223
	v_max_i32_e32 v2, 0xffffff80, v3
	s_waitcnt vmcnt(1)
	v_add_f32_e32 v3, v23, v23
	v_floor_f32_e32 v3, v3
	v_add_u32_e32 v2, 0x80, v2
	v_cvt_i32_f32_e32 v3, v3
	v_min_u32_e32 v2, 0xff, v2
	v_cndmask_b32_e64 v2, v2, v226, s[30:31]
	v_lshl_add_u32 v2, v2, 2, s6
	ds_add_u32 v2, v223
	v_max_i32_e32 v2, 0xffffff80, v3
	s_waitcnt vmcnt(0)
	v_add_f32_e32 v3, v24, v24
	v_floor_f32_e32 v3, v3
	v_add_u32_e32 v2, 0x80, v2
	v_cvt_i32_f32_e32 v3, v3
	v_min_u32_e32 v2, 0xff, v2
	v_cndmask_b32_e64 v2, v2, v226, s[34:35]
	v_lshl_add_u32 v2, v2, 2, s6
	ds_add_u32 v2, v223
	v_max_i32_e32 v2, 0xffffff80, v3
	v_add_u32_e32 v2, 0x80, v2
	v_min_u32_e32 v2, 0xff, v2
	v_cndmask_b32_e64 v2, v2, v226, s[36:37]
	v_lshl_add_u32 v2, v2, 2, s6
	ds_add_u32 v2, v223
	s_waitcnt lgkmcnt(0)
	ds_read_b128 v[2:5], v7
	v_readlane_b32 s8, v254, 12
	v_readlane_b32 s9, v254, 13
	s_waitcnt lgkmcnt(0)
	v_add_u32_e32 v26, v2, v3
	v_add3_u32 v27, v26, v4, v5
	v_mov_b32_e32 v26, v27
	s_nop 1
	v_add_u32_dpp v26, v26, v26 row_shr:1 row_mask:0xf bank_mask:0xf bound_ctrl:0
	s_nop 1
	v_add_u32_dpp v26, v26, v26 row_shr:2 row_mask:0xf bank_mask:0xf bound_ctrl:0
	s_nop 1
	v_add_u32_dpp v26, v26, v26 row_shr:4 row_mask:0xf bank_mask:0xf bound_ctrl:0
	s_nop 1
	v_add_u32_dpp v26, v26, v26 row_shr:8 row_mask:0xf bank_mask:0xf bound_ctrl:0
	s_nop 1
	v_add_u32_dpp v26, v26, v26 row_bcast:15 row_mask:0xa bank_mask:0xf
	s_nop 1
	v_add_u32_dpp v26, v26, v26 row_bcast:31 row_mask:0xc bank_mask:0xf
	s_nop 1
	v_readlane_b32 s8, v26, 63
	s_nop 1
	v_sub_u32_e32 v28, s8, v26
	v_add_u32_e32 v26, v28, v27
	v_mov_b32_e32 v27, v28
	v_add_u32_e32 v30, v27, v5
	v_cmp_gt_u32_e32 vcc, s63, v30
	v_mov_b32_e32 v28, 3
	v_mov_b32_e32 v29, v27
	s_and_saveexec_b64 s[8:9], vcc
	s_mov_b32 s88, 0xefa18f08
	s_cbranch_execz .LBB0_658
; #define LAS __attribute__((address_space(3)))
; template <int NJ>
; __device__ __forceinline__ void select_rows(const GAS float* sr0, GAS unsigned long long* mb0, LAS unsigned* hist, LAS unsigned* kbuf, int ntl, int lane) {
;     ...
;             key[j] = ok ? skey_of(f) : 0u;
;             const int bk = min(max((int)floorf(f + f) + 128, 0), 255);
;             __hip_atomic_fetch_add(hist + (ok ? bk : 256), 1u, __ATOMIC_RELAXED, __HIP_MEMORY_SCOPE_WORKGROUP);
;         }
;         __builtin_amdgcn_wave_barrier();
;         asm volatile("s_waitcnt lgkmcnt(0)" ::: "memory");
;         unsigned B, rem, C;
;         {
;             const u32x4 hv = *(const LAS u32x4*)(hist + 4 * lane);
;             const unsigned s4 = hv.x + hv.y + hv.z + hv.w;
;             unsigned S = s4;
; #pragma unroll
;             for (int off = 1; off < 64; off <<= 1) { const unsigned n = __shfl_down(S, off); if (lane + off < 64) S += n; }
;             const unsigned excl = S - s4;
;             const bool mine = (excl < 256u) && (256u <= S);
;             unsigned dl, above, cnt, c = excl;
;             if (c + hv.w >= 256u) { dl = 3; above = c; cnt = hv.w; } else { c += hv.w; if (c + hv.z >= 256u) { dl = 2; above = c; cnt = hv.z; } else { c += hv.z; if (c + hv.y >= 256u) { dl = 1; above = c; cnt = hv.y; } else { c += hv.y; dl = 0; above = c; cnt = hv.x; } } }
;             const unsigned long long bm = __ballot(mine);
;             const int src = bm ? (int)__builtin_ctzll(bm) : 0;
;             B = (unsigned)__builtin_amdgcn_readlane((int)(4 * lane + dl), src);
;             rem = 256u - (unsigned)__builtin_amdgcn_readlane((int)above, src);
;             C = (unsigned)__builtin_amdgcn_readlane((int)cnt, src);
;         }
;         const unsigned klo = (B == 0u) ? 1u : skey_of((float)((int)B - 128) * 0.5f);
;         const unsigned khi = (B == 255u) ? 0xffffffffu : skey_of((float)((int)B - 127) * 0.5f);
;         const unsigned range = khi - klo;
;         unsigned tau = 0u, remf = 0u, cnteq = 0u; bool generic = C > 64u;
;         if (!generic) {
; #pragma unroll
;             for (int j = 0; j < NJ; ++j) {
;                 if ((key[j] - klo) < range) { const unsigned slot = __hip_atomic_fetch_add(hist + 257, 1u, __ATOMIC_RELAXED, __HIP_MEMORY_SCOPE_WORKGROUP); hist[258 + (slot & 63u)] = key[j]; }
;             }
	v_add_u32_e32 v5, v30, v4
	v_cmp_gt_u32_e32 vcc, s63, v5
	v_mov_b32_e32 v28, 2
	s_and_saveexec_b64 s[38:39], vcc
	v_add_u32_e32 v4, v5, v3
	s_movk_i32 s40, 0xff
	v_cmp_lt_u32_e32 vcc, s40, v4
	s_nop 1
	v_cndmask_b32_e64 v28, 0, 1, vcc
	v_cndmask_b32_e32 v30, v4, v5, vcc
	v_cndmask_b32_e32 v4, v2, v3, vcc
	s_or_b64 exec, exec, s[38:39]
	v_mov_b32_e32 v5, v4
	v_mov_b32_e32 v29, v30
.LBB0_658:
	s_or_b64 exec, exec, s[8:9]
	v_ashrrev_i32_e32 v2, 31, v25
	s_brev_b32 s8, 1
	v_bitop3_b32 v2, v2, v25, s8 bitop3:0x36
	v_cndmask_b32_e64 v4, v2, 0, s[0:1]
	v_ashrrev_i32_e32 v2, 31, v10
	v_bitop3_b32 v2, v2, v10, s8 bitop3:0x36
	v_cndmask_b32_e64 v10, v2, 0, s[2:3]
	v_ashrrev_i32_e32 v2, 31, v11
	v_bitop3_b32 v2, v2, v11, s8 bitop3:0x36
	v_cndmask_b32_e64 v11, v2, 0, s[4:5]
	v_ashrrev_i32_e32 v2, 31, v12
	v_bitop3_b32 v2, v2, v12, s8 bitop3:0x36
	v_cndmask_b32_e64 v12, v2, 0, s[10:11]
	v_ashrrev_i32_e32 v2, 31, v13
	v_bitop3_b32 v2, v2, v13, s8 bitop3:0x36
	v_cndmask_b32_e64 v13, v2, 0, s[12:13]
	v_ashrrev_i32_e32 v2, 31, v14
	v_bitop3_b32 v2, v2, v14, s8 bitop3:0x36
	v_cndmask_b32_e64 v14, v2, 0, s[14:15]
	v_ashrrev_i32_e32 v2, 31, v15
	v_bitop3_b32 v2, v2, v15, s8 bitop3:0x36
	v_cndmask_b32_e64 v15, v2, 0, s[16:17]
	v_ashrrev_i32_e32 v2, 31, v16
	v_bitop3_b32 v2, v2, v16, s8 bitop3:0x36
	v_cndmask_b32_e64 v16, v2, 0, s[18:19]
	v_ashrrev_i32_e32 v2, 31, v17
	v_bitop3_b32 v2, v2, v17, s8 bitop3:0x36
	v_cndmask_b32_e64 v17, v2, 0, s[52:53]
	v_ashrrev_i32_e32 v2, 31, v18
	v_bitop3_b32 v2, v2, v18, s8 bitop3:0x36
	v_cndmask_b32_e64 v18, v2, 0, s[54:55]
	v_ashrrev_i32_e32 v2, 31, v19
	v_bitop3_b32 v2, v2, v19, s8 bitop3:0x36
	v_cndmask_b32_e64 v19, v2, 0, s[24:25]
	v_ashrrev_i32_e32 v2, 31, v20
	v_bitop3_b32 v2, v2, v20, s8 bitop3:0x36
	v_cndmask_b32_e64 v20, v2, 0, s[26:27]
	v_ashrrev_i32_e32 v2, 31, v21
	v_bitop3_b32 v2, v2, v21, s8 bitop3:0x36
	v_cndmask_b32_e64 v21, v2, 0, s[28:29]
	v_ashrrev_i32_e32 v2, 31, v22
	v_bitop3_b32 v2, v2, v22, s8 bitop3:0x36
	v_cndmask_b32_e64 v22, v2, 0, s[30:31]
	v_ashrrev_i32_e32 v2, 31, v23
	v_bitop3_b32 v2, v2, v23, s8 bitop3:0x36
	v_cndmask_b32_e64 v23, v2, 0, s[34:35]
	v_ashrrev_i32_e32 v2, 31, v24
	v_bitop3_b32 v2, v2, v24, s8 bitop3:0x36
	s_movk_i32 s8, 0xff
	v_cmp_gt_u32_e32 vcc, s63, v27
	v_cmp_lt_u32_e64 s[8:9], s8, v26
	s_and_b64 s[8:9], s[8:9], vcc
	v_cndmask_b32_e64 v24, v2, 0, s[36:37]
	v_cndmask_b32_e64 v2, 0, 1, s[8:9]
	v_cmp_ne_u32_e32 vcc, 0, v2
	s_ff1_i32_b64 s8, vcc
	s_cmp_lg_u64 vcc, 0
	s_cselect_b32 s8, s8, 0
	v_or_b32_e32 v2, v28, v6
	v_readlane_b32 s43, v5, s8
	v_readlane_b32 s38, v2, s8
	v_readlane_b32 s42, v29, s8
	s_cmp_gt_u32 s43, 64
	s_mov_b64 s[8:9], -1
	s_cbranch_scc1 .LBB0_729
	s_add_i32 s8, s38, 0xffffff80
	v_cvt_f32_i32_e32 v2, s8
	s_cmp_lg_u32 s38, 0
	s_cselect_b64 vcc, -1, 0
	s_add_i32 s8, s38, 0xffffff81
	v_mul_f32_e32 v2, 0.5, v2
	v_ashrrev_i32_e32 v3, 31, v2
	v_or_b32_e32 v3, 0x80000000, v3
	v_xor_b32_e32 v2, v3, v2
	v_cvt_f32_i32_e32 v3, s8
	s_cmpk_lg_i32 s38, 0xff
	v_cndmask_b32_e32 v2, 1, v2, vcc
	s_cselect_b64 vcc, -1, 0
	v_mul_f32_e32 v3, 0.5, v3
	v_ashrrev_i32_e32 v5, 31, v3
	v_or_b32_e32 v5, 0x80000000, v5
	v_xor_b32_e32 v3, v5, v3
	v_cndmask_b32_e32 v3, -1, v3, vcc
	v_sub_u32_e32 v3, v3, v2
	v_sub_u32_e32 v5, v4, v2
	v_cmp_lt_u32_e32 vcc, v5, v3
	s_and_saveexec_b64 s[8:9], vcc
	s_cbranch_execz .LBB0_663
	s_mov_b64 s[40:41], exec
	v_mbcnt_lo_u32_b32 v5, s40, 0
	v_mbcnt_hi_u32_b32 v5, s41, v5
	s_bcnt1_i32_b64 s40, s[40:41]
	s_mov_b32 s38, s100
	s_add_i32 s100, s100, s40
	v_add_u32_e32 v5, s38, v5
	v_and_b32_e32 v5, 63, v5
	v_lshl_add_u32 v5, v5, 2, s6
	ds_write_b32 v5, v4 offset:1032
.LBB0_663:
	s_or_b64 exec, exec, s[8:9]
	v_sub_u32_e32 v5, v10, v2
	v_cmp_lt_u32_e32 vcc, v5, v3
	s_and_saveexec_b64 s[8:9], vcc
	s_cbranch_execz .LBB0_667
	s_mov_b64 s[40:41], exec
	v_mbcnt_lo_u32_b32 v5, s40, 0
	v_mbcnt_hi_u32_b32 v5, s41, v5
	s_bcnt1_i32_b64 s40, s[40:41]
	s_mov_b32 s38, s100
	s_add_i32 s100, s100, s40
	v_add_u32_e32 v5, s38, v5
	v_and_b32_e32 v5, 63, v5
	v_lshl_add_u32 v5, v5, 2, s6
	ds_write_b32 v5, v10 offset:1032
.LBB0_667:
	s_or_b64 exec, exec, s[8:9]
	v_sub_u32_e32 v5, v11, v2
	v_cmp_lt_u32_e32 vcc, v5, v3
	s_and_saveexec_b64 s[8:9], vcc
	s_cbranch_execz .LBB0_671
	s_mov_b64 s[40:41], exec
	v_mbcnt_lo_u32_b32 v5, s40, 0
	v_mbcnt_hi_u32_b32 v5, s41, v5
	s_bcnt1_i32_b64 s40, s[40:41]
	s_mov_b32 s38, s100
	s_add_i32 s100, s100, s40
	v_add_u32_e32 v5, s38, v5
	v_and_b32_e32 v5, 63, v5
	v_lshl_add_u32 v5, v5, 2, s6
	ds_write_b32 v5, v11 offset:1032
.LBB0_671:
	s_or_b64 exec, exec, s[8:9]
	v_sub_u32_e32 v5, v12, v2
	v_cmp_lt_u32_e32 vcc, v5, v3
	s_and_saveexec_b64 s[8:9], vcc
	s_cbranch_execz .LBB0_675
	s_mov_b64 s[40:41], exec
	v_mbcnt_lo_u32_b32 v5, s40, 0
	v_mbcnt_hi_u32_b32 v5, s41, v5
	s_bcnt1_i32_b64 s40, s[40:41]
	s_mov_b32 s38, s100
	s_add_i32 s100, s100, s40
	v_add_u32_e32 v5, s38, v5
	v_and_b32_e32 v5, 63, v5
	v_lshl_add_u32 v5, v5, 2, s6
	ds_write_b32 v5, v12 offset:1032
; template <int NJ>
; __device__ __forceinline__ void select_rows(const GAS float* sr0, GAS unsigned long long* mb0, LAS unsigned* hist, LAS unsigned* kbuf, int ntl, int lane) {
;     ...
;             for (int j = 0; j < NJ; ++j) {
;                 if ((key[j] - klo) < range) { const unsigned slot = __hip_atomic_fetch_add(hist + 257, 1u, __ATOMIC_RELAXED, __HIP_MEMORY_SCOPE_WORKGROUP); hist[258 + (slot & 63u)] = key[j]; }
;             }
;             __builtin_amdgcn_wave_barrier();
;             asm volatile("s_waitcnt lgkmcnt(0)" ::: "memory");
.LBB0_675:
	s_or_b64 exec, exec, s[8:9]
	v_sub_u32_e32 v5, v13, v2
	v_cmp_lt_u32_e32 vcc, v5, v3
	s_and_saveexec_b64 s[8:9], vcc
	s_cbranch_execz .LBB0_679
	s_mov_b64 s[40:41], exec
	v_mbcnt_lo_u32_b32 v5, s40, 0
	v_mbcnt_hi_u32_b32 v5, s41, v5
	s_bcnt1_i32_b64 s40, s[40:41]
	s_mov_b32 s38, s100
	s_add_i32 s100, s100, s40
	v_add_u32_e32 v5, s38, v5
	v_and_b32_e32 v5, 63, v5
	v_lshl_add_u32 v5, v5, 2, s6
	ds_write_b32 v5, v13 offset:1032
.LBB0_679:
	s_or_b64 exec, exec, s[8:9]
	v_sub_u32_e32 v5, v14, v2
	v_cmp_lt_u32_e32 vcc, v5, v3
	s_and_saveexec_b64 s[8:9], vcc
	s_cbranch_execz .LBB0_683
	s_mov_b64 s[40:41], exec
	v_mbcnt_lo_u32_b32 v5, s40, 0
	v_mbcnt_hi_u32_b32 v5, s41, v5
	s_bcnt1_i32_b64 s40, s[40:41]
	s_mov_b32 s38, s100
	s_add_i32 s100, s100, s40
	v_add_u32_e32 v5, s38, v5
	v_and_b32_e32 v5, 63, v5
	v_lshl_add_u32 v5, v5, 2, s6
	ds_write_b32 v5, v14 offset:1032
.LBB0_683:
	s_or_b64 exec, exec, s[8:9]
	v_sub_u32_e32 v5, v15, v2
	v_cmp_lt_u32_e32 vcc, v5, v3
	s_and_saveexec_b64 s[8:9], vcc
	s_cbranch_execz .LBB0_687
	s_mov_b64 s[40:41], exec
	v_mbcnt_lo_u32_b32 v5, s40, 0
	v_mbcnt_hi_u32_b32 v5, s41, v5
	s_bcnt1_i32_b64 s40, s[40:41]
	s_mov_b32 s38, s100
	s_add_i32 s100, s100, s40
	v_add_u32_e32 v5, s38, v5
	v_and_b32_e32 v5, 63, v5
	v_lshl_add_u32 v5, v5, 2, s6
	ds_write_b32 v5, v15 offset:1032
.LBB0_687:
	s_or_b64 exec, exec, s[8:9]
	v_sub_u32_e32 v5, v16, v2
	v_cmp_lt_u32_e32 vcc, v5, v3
	s_and_saveexec_b64 s[8:9], vcc
	s_cbranch_execz .LBB0_691
	s_mov_b64 s[40:41], exec
	v_mbcnt_lo_u32_b32 v5, s40, 0
	v_mbcnt_hi_u32_b32 v5, s41, v5
	s_bcnt1_i32_b64 s40, s[40:41]
	s_mov_b32 s38, s100
	s_add_i32 s100, s100, s40
	v_add_u32_e32 v5, s38, v5
	v_and_b32_e32 v5, 63, v5
	v_lshl_add_u32 v5, v5, 2, s6
	ds_write_b32 v5, v16 offset:1032
.LBB0_691:
	s_or_b64 exec, exec, s[8:9]
	v_sub_u32_e32 v5, v17, v2
	v_cmp_lt_u32_e32 vcc, v5, v3
	s_and_saveexec_b64 s[8:9], vcc
	s_cbranch_execz .LBB0_695
	s_mov_b64 s[40:41], exec
	v_mbcnt_lo_u32_b32 v5, s40, 0
	v_mbcnt_hi_u32_b32 v5, s41, v5
	s_bcnt1_i32_b64 s40, s[40:41]
	s_mov_b32 s38, s100
	s_add_i32 s100, s100, s40
	v_add_u32_e32 v5, s38, v5
	v_and_b32_e32 v5, 63, v5
	v_lshl_add_u32 v5, v5, 2, s6
	ds_write_b32 v5, v17 offset:1032
.LBB0_695:
	s_or_b64 exec, exec, s[8:9]
	v_sub_u32_e32 v5, v18, v2
	v_cmp_lt_u32_e32 vcc, v5, v3
	s_and_saveexec_b64 s[8:9], vcc
	s_cbranch_execz .LBB0_699
	s_mov_b64 s[40:41], exec
	v_mbcnt_lo_u32_b32 v5, s40, 0
	v_mbcnt_hi_u32_b32 v5, s41, v5
	s_bcnt1_i32_b64 s40, s[40:41]
	s_mov_b32 s38, s100
	s_add_i32 s100, s100, s40
	v_add_u32_e32 v5, s38, v5
	v_and_b32_e32 v5, 63, v5
	v_lshl_add_u32 v5, v5, 2, s6
	ds_write_b32 v5, v18 offset:1032
.LBB0_699:
	s_or_b64 exec, exec, s[8:9]
	v_sub_u32_e32 v5, v19, v2
	v_cmp_lt_u32_e32 vcc, v5, v3
	s_and_saveexec_b64 s[8:9], vcc
	s_cbranch_execz .LBB0_703
	s_mov_b64 s[40:41], exec
	v_mbcnt_lo_u32_b32 v5, s40, 0
	v_mbcnt_hi_u32_b32 v5, s41, v5
	s_bcnt1_i32_b64 s40, s[40:41]
	s_mov_b32 s38, s100
	s_add_i32 s100, s100, s40
	v_add_u32_e32 v5, s38, v5
	v_and_b32_e32 v5, 63, v5
	v_lshl_add_u32 v5, v5, 2, s6
	ds_write_b32 v5, v19 offset:1032
.LBB0_703:
	s_or_b64 exec, exec, s[8:9]
	v_sub_u32_e32 v5, v20, v2
	v_cmp_lt_u32_e32 vcc, v5, v3
	s_and_saveexec_b64 s[8:9], vcc
	s_cbranch_execz .LBB0_707
	s_mov_b64 s[40:41], exec
	v_mbcnt_lo_u32_b32 v5, s40, 0
	v_mbcnt_hi_u32_b32 v5, s41, v5
	s_bcnt1_i32_b64 s40, s[40:41]
	s_mov_b32 s38, s100
	s_add_i32 s100, s100, s40
	v_add_u32_e32 v5, s38, v5
	v_and_b32_e32 v5, 63, v5
	v_lshl_add_u32 v5, v5, 2, s6
	ds_write_b32 v5, v20 offset:1032
.LBB0_707:
	s_or_b64 exec, exec, s[8:9]
	v_sub_u32_e32 v5, v21, v2
	v_cmp_lt_u32_e32 vcc, v5, v3
	s_and_saveexec_b64 s[8:9], vcc
	s_cbranch_execz .LBB0_711
	s_mov_b64 s[40:41], exec
	v_mbcnt_lo_u32_b32 v5, s40, 0
	v_mbcnt_hi_u32_b32 v5, s41, v5
	s_bcnt1_i32_b64 s40, s[40:41]
	s_mov_b32 s38, s100
	s_add_i32 s100, s100, s40
	v_add_u32_e32 v5, s38, v5
	v_and_b32_e32 v5, 63, v5
	v_lshl_add_u32 v5, v5, 2, s6
	ds_write_b32 v5, v21 offset:1032
.LBB0_711:
	s_or_b64 exec, exec, s[8:9]
	v_sub_u32_e32 v5, v22, v2
	v_cmp_lt_u32_e32 vcc, v5, v3
	s_and_saveexec_b64 s[8:9], vcc
	s_cbranch_execz .LBB0_715
	s_mov_b64 s[40:41], exec
	v_mbcnt_lo_u32_b32 v5, s40, 0
	v_mbcnt_hi_u32_b32 v5, s41, v5
	s_bcnt1_i32_b64 s40, s[40:41]
	s_mov_b32 s38, s100
	s_add_i32 s100, s100, s40
	v_add_u32_e32 v5, s38, v5
	v_and_b32_e32 v5, 63, v5
	v_lshl_add_u32 v5, v5, 2, s6
	ds_write_b32 v5, v22 offset:1032
.LBB0_715:
	s_or_b64 exec, exec, s[8:9]
	v_sub_u32_e32 v5, v23, v2
	v_cmp_lt_u32_e32 vcc, v5, v3
	s_and_saveexec_b64 s[8:9], vcc
	s_cbranch_execz .LBB0_719
	s_mov_b64 s[40:41], exec
	v_mbcnt_lo_u32_b32 v5, s40, 0
	v_mbcnt_hi_u32_b32 v5, s41, v5
	s_bcnt1_i32_b64 s40, s[40:41]
	s_mov_b32 s38, s100
	s_add_i32 s100, s100, s40
	v_add_u32_e32 v5, s38, v5
	v_and_b32_e32 v5, 63, v5
	v_lshl_add_u32 v5, v5, 2, s6
	ds_write_b32 v5, v23 offset:1032
.LBB0_719:
	s_or_b64 exec, exec, s[8:9]
	v_sub_u32_e32 v2, v24, v2
	v_cmp_lt_u32_e32 vcc, v2, v3
	s_and_saveexec_b64 s[8:9], vcc
	s_cbranch_execz .LBB0_723
	s_mov_b64 s[40:41], exec
	v_mbcnt_lo_u32_b32 v2, s40, 0
	v_mbcnt_hi_u32_b32 v2, s41, v2
	s_bcnt1_i32_b64 s40, s[40:41]
	s_mov_b32 s38, s100
	s_add_i32 s100, s100, s40
	v_add_u32_e32 v2, s38, v2
	v_and_b32_e32 v2, 63, v2
	v_lshl_add_u32 v2, v2, 2, s6
	ds_write_b32 v2, v24 offset:1032

; #define LAS __attribute__((address_space(3)))
; #define GAS __attribute__((address_space(1)))
; __device__ __forceinline__ unsigned skey_of(float f) { const unsigned u = __float_as_uint(f); return u ^ ((unsigned)((int)u >> 31) | 0x80000000u); }
; template <int NJ>
; __device__ __forceinline__ void select_rows(const GAS float* sr0, GAS unsigned long long* mb0, LAS unsigned* hist, LAS unsigned* kbuf, int ntl, int lane) {
;     ...
;     for (int rr = 0; rr < 8; ++rr) {
;         const GAS float* srow = sr0 + (size_t)rr * SEQ;
;         float fv[NJ];
; #pragma unroll
;         for (int j = 0; j < NJ; ++j) fv[j] = srow[64 * j];
;         { unsigned z = 0u; asm volatile("" : "+v"(z));
;           *(LAS u32x4*)(hist + 4 * lane) = (u32x4){z, z, z, z}; if (lane < 2) hist[256 + lane] = z; }
;         __builtin_amdgcn_wave_barrier();
;         unsigned key[NJ];
; #pragma unroll
;         for (int j = 0; j < NJ; ++j) {
;             const float f = fv[j]; const bool ok = (vm >> j) & 1u;
;             key[j] = ok ? skey_of(f) : 0u;
;             const int bk = min(max((int)floorf(f + f) + 128, 0), 255);
;             __hip_atomic_fetch_add(hist + (ok ? bk : 256), 1u, __ATOMIC_RELAXED, __HIP_MEMORY_SCOPE_WORKGROUP);
;         }
;         __builtin_amdgcn_wave_barrier();
;         asm volatile("s_waitcnt lgkmcnt(0)" ::: "memory");
;         unsigned B, rem, C;
;         {
;             const u32x4 hv = *(const LAS u32x4*)(hist + 4 * lane);
;             const unsigned s4 = hv.x + hv.y + hv.z + hv.w;
;             unsigned S = s4;
; #pragma unroll
;             for (int off = 1; off < 64; off <<= 1) { const unsigned n = __shfl_down(S, off); if (lane + off < 64) S += n; }
;             const unsigned excl = S - s4;
;             const bool mine = (excl < 256u) && (256u <= S);
;             unsigned dl, above, cnt, c = excl;
;             if (c + hv.w >= 256u) { dl = 3; above = c; cnt = hv.w; } else { c += hv.w; if (c + hv.z >= 256u) { dl = 2; above = c; cnt = hv.z; } else { c += hv.z; if (c + hv.y >= 256u) { dl = 1; above = c; cnt = hv.y; } else { c += hv.y; dl = 0; above = c; cnt = hv.x; } } }
.LBB0_739:
	s_mov_b32 s100, 0
	s_lshl_b32 s88, s7, 11
	v_lshl_add_u64 v[2:3], s[88:89], 2, v[8:9]
	global_load_dword v17, v[2:3], off
	global_load_dword v10, v[2:3], off offset:256
	global_load_dword v11, v[2:3], off offset:512
	global_load_dword v12, v[2:3], off offset:768
	global_load_dword v13, v[2:3], off offset:1024
	global_load_dword v14, v[2:3], off offset:1280
	global_load_dword v15, v[2:3], off offset:1536
	global_load_dword v16, v[2:3], off offset:1792
	v_mov_b32_e32 v2, 0
	s_nop 0
	v_mov_b32_e32 v3, v2
	v_mov_b32_e32 v4, v2
	v_mov_b32_e32 v5, v2
	ds_write_b128 v7, v[2:5]
	s_and_saveexec_b64 s[8:9], s[74:75]
	v_add_u32_e32 v3, v7, v38
	ds_write_b32 v3, v2 offset:1024
	s_or_b64 exec, exec, s[8:9]
	s_waitcnt vmcnt(7)
	v_add_f32_e32 v2, v17, v17
	v_floor_f32_e32 v2, v2
	v_cvt_i32_f32_e32 v2, v2
	s_waitcnt vmcnt(6)
	v_add_f32_e32 v3, v10, v10
	v_floor_f32_e32 v3, v3
	v_cvt_i32_f32_e32 v3, v3
	v_max_i32_e32 v2, 0xffffff80, v2
	v_add_u32_e32 v2, 0x80, v2
	v_min_u32_e32 v2, 0xff, v2
	v_cndmask_b32_e64 v2, v2, v226, s[0:1]
	v_lshl_add_u32 v2, v2, 2, s6
	ds_add_u32 v2, v223
	v_max_i32_e32 v2, 0xffffff80, v3
	s_waitcnt vmcnt(5)
	v_add_f32_e32 v3, v11, v11
	v_floor_f32_e32 v3, v3
	v_add_u32_e32 v2, 0x80, v2
	v_cvt_i32_f32_e32 v3, v3
	v_min_u32_e32 v2, 0xff, v2
	v_cndmask_b32_e64 v2, v2, v226, s[2:3]
	v_lshl_add_u32 v2, v2, 2, s6
	ds_add_u32 v2, v223
	v_max_i32_e32 v2, 0xffffff80, v3
	s_waitcnt vmcnt(4)
	v_add_f32_e32 v3, v12, v12
	v_floor_f32_e32 v3, v3
	v_add_u32_e32 v2, 0x80, v2
	v_cvt_i32_f32_e32 v3, v3
	v_min_u32_e32 v2, 0xff, v2
	v_cndmask_b32_e64 v2, v2, v226, s[4:5]
	v_lshl_add_u32 v2, v2, 2, s6
	ds_add_u32 v2, v223
	v_max_i32_e32 v2, 0xffffff80, v3
	s_waitcnt vmcnt(3)
	v_add_f32_e32 v3, v13, v13
	v_floor_f32_e32 v3, v3
	v_add_u32_e32 v2, 0x80, v2
	v_cvt_i32_f32_e32 v3, v3
	v_min_u32_e32 v2, 0xff, v2
	v_cndmask_b32_e64 v2, v2, v226, s[10:11]
	v_lshl_add_u32 v2, v2, 2, s6
	ds_add_u32 v2, v223
	v_max_i32_e32 v2, 0xffffff80, v3
	s_waitcnt vmcnt(2)
	v_add_f32_e32 v3, v14, v14
	v_floor_f32_e32 v3, v3
	v_add_u32_e32 v2, 0x80, v2
	v_cvt_i32_f32_e32 v3, v3
	v_min_u32_e32 v2, 0xff, v2
	v_cndmask_b32_e64 v2, v2, v226, s[12:13]
	v_lshl_add_u32 v2, v2, 2, s6
	ds_add_u32 v2, v223
	v_max_i32_e32 v2, 0xffffff80, v3
	s_waitcnt vmcnt(1)
	v_add_f32_e32 v3, v15, v15
	v_floor_f32_e32 v3, v3
	v_add_u32_e32 v2, 0x80, v2
	v_cvt_i32_f32_e32 v3, v3
	v_min_u32_e32 v2, 0xff, v2
	v_cndmask_b32_e64 v2, v2, v226, s[14:15]
	v_lshl_add_u32 v2, v2, 2, s6
	ds_add_u32 v2, v223
	v_max_i32_e32 v2, 0xffffff80, v3
	s_waitcnt vmcnt(0)
	v_add_f32_e32 v3, v16, v16
	v_floor_f32_e32 v3, v3
	v_add_u32_e32 v2, 0x80, v2
	v_cvt_i32_f32_e32 v3, v3
	v_min_u32_e32 v2, 0xff, v2
	v_cndmask_b32_e64 v2, v2, v226, s[16:17]
	v_lshl_add_u32 v2, v2, 2, s6
	ds_add_u32 v2, v223
	v_max_i32_e32 v2, 0xffffff80, v3
	v_add_u32_e32 v2, 0x80, v2
	v_min_u32_e32 v2, 0xff, v2
	v_cndmask_b32_e64 v2, v2, v226, s[18:19]
	v_lshl_add_u32 v2, v2, 2, s6
	ds_add_u32 v2, v223
	s_waitcnt lgkmcnt(0)
	ds_read_b128 v[2:5], v7
	v_readlane_b32 s8, v254, 12
	v_readlane_b32 s9, v254, 13
	s_waitcnt lgkmcnt(0)
	v_add_u32_e32 v18, v2, v3
	v_add3_u32 v19, v18, v4, v5
	v_mov_b32_e32 v18, v19
	s_nop 1
	v_add_u32_dpp v18, v18, v18 row_shr:1 row_mask:0xf bank_mask:0xf bound_ctrl:0
	s_nop 1
	v_add_u32_dpp v18, v18, v18 row_shr:2 row_mask:0xf bank_mask:0xf bound_ctrl:0
	s_nop 1
	v_add_u32_dpp v18, v18, v18 row_shr:4 row_mask:0xf bank_mask:0xf bound_ctrl:0
	s_nop 1
	v_add_u32_dpp v18, v18, v18 row_shr:8 row_mask:0xf bank_mask:0xf bound_ctrl:0
	s_nop 1
	v_add_u32_dpp v18, v18, v18 row_bcast:15 row_mask:0xa bank_mask:0xf
	s_nop 1
	v_add_u32_dpp v18, v18, v18 row_bcast:31 row_mask:0xc bank_mask:0xf
	s_nop 1
	v_readlane_b32 s8, v18, 63
	s_nop 1
	v_sub_u32_e32 v20, s8, v18
	v_add_u32_e32 v18, v20, v19
	v_mov_b32_e32 v19, v20
	v_add_u32_e32 v22, v19, v5
	v_cmp_gt_u32_e32 vcc, s63, v22
	v_mov_b32_e32 v20, 3
	v_mov_b32_e32 v21, v19
	s_and_saveexec_b64 s[8:9], vcc
	s_mov_b32 s88, 0xefa18f08
	s_cbranch_execz .LBB0_745
	v_add_u32_e32 v5, v22, v4
	v_cmp_gt_u32_e32 vcc, s63, v5
	v_mov_b32_e32 v20, 2
	s_and_saveexec_b64 s[48:49], vcc
	v_add_u32_e32 v4, v5, v3
	s_movk_i32 s50, 0xff
	v_cmp_lt_u32_e32 vcc, s50, v4
	s_nop 1
	v_cndmask_b32_e64 v20, 0, 1, vcc
	v_cndmask_b32_e32 v22, v4, v5, vcc
	v_cndmask_b32_e32 v4, v2, v3, vcc
	s_or_b64 exec, exec, s[48:49]
	v_mov_b32_e32 v5, v4
	v_mov_b32_e32 v21, v22
; #define LAS __attribute__((address_space(3)))
; template <int NJ>
; __device__ __forceinline__ void select_rows(const GAS float* sr0, GAS unsigned long long* mb0, LAS unsigned* hist, LAS unsigned* kbuf, int ntl, int lane) {
;     ...
;             key[j] = ok ? skey_of(f) : 0u;
;             const int bk = min(max((int)floorf(f + f) + 128, 0), 255);
;             __hip_atomic_fetch_add(hist + (ok ? bk : 256), 1u, __ATOMIC_RELAXED, __HIP_MEMORY_SCOPE_WORKGROUP);
;         }
;         __builtin_amdgcn_wave_barrier();
;         asm volatile("s_waitcnt lgkmcnt(0)" ::: "memory");
;         unsigned B, rem, C;
;         {
;             const u32x4 hv = *(const LAS u32x4*)(hist + 4 * lane);
;             const unsigned s4 = hv.x + hv.y + hv.z + hv.w;
;             unsigned S = s4;
; #pragma unroll
;             for (int off = 1; off < 64; off <<= 1) { const unsigned n = __shfl_down(S, off); if (lane + off < 64) S += n; }
;             const unsigned excl = S - s4;
;             const bool mine = (excl < 256u) && (256u <= S);
;             unsigned dl, above, cnt, c = excl;
;             if (c + hv.w >= 256u) { dl = 3; above = c; cnt = hv.w; } else { c += hv.w; if (c + hv.z >= 256u) { dl = 2; above = c; cnt = hv.z; } else { c += hv.z; if (c + hv.y >= 256u) { dl = 1; above = c; cnt = hv.y; } else { c += hv.y; dl = 0; above = c; cnt = hv.x; } } }
;             const unsigned long long bm = __ballot(mine);
;             const int src = bm ? (int)__builtin_ctzll(bm) : 0;
;             B = (unsigned)__builtin_amdgcn_readlane((int)(4 * lane + dl), src);
;             rem = 256u - (unsigned)__builtin_amdgcn_readlane((int)above, src);
;             C = (unsigned)__builtin_amdgcn_readlane((int)cnt, src);
;         }
;         const unsigned klo = (B == 0u) ? 1u : skey_of((float)((int)B - 128) * 0.5f);
;         const unsigned khi = (B == 255u) ? 0xffffffffu : skey_of((float)((int)B - 127) * 0.5f);
;         const unsigned range = khi - klo;
;         unsigned tau = 0u, remf = 0u, cnteq = 0u; bool generic = C > 64u;
;         if (!generic) {
; #pragma unroll
;             for (int j = 0; j < NJ; ++j) {
;                 if ((key[j] - klo) < range) { const unsigned slot = __hip_atomic_fetch_add(hist + 257, 1u, __ATOMIC_RELAXED, __HIP_MEMORY_SCOPE_WORKGROUP); hist[258 + (slot & 63u)] = key[j]; }
;             }
.LBB0_745:
	s_or_b64 exec, exec, s[8:9]
	v_ashrrev_i32_e32 v2, 31, v17
	s_brev_b32 s8, 1
	v_bitop3_b32 v2, v2, v17, s8 bitop3:0x36
	v_cndmask_b32_e64 v4, v2, 0, s[0:1]
	v_ashrrev_i32_e32 v2, 31, v10
	v_bitop3_b32 v2, v2, v10, s8 bitop3:0x36
	v_cndmask_b32_e64 v10, v2, 0, s[2:3]
	v_ashrrev_i32_e32 v2, 31, v11
	v_bitop3_b32 v2, v2, v11, s8 bitop3:0x36
	v_cndmask_b32_e64 v11, v2, 0, s[4:5]
	v_ashrrev_i32_e32 v2, 31, v12
	v_bitop3_b32 v2, v2, v12, s8 bitop3:0x36
	v_cndmask_b32_e64 v12, v2, 0, s[10:11]
	v_ashrrev_i32_e32 v2, 31, v13
	v_bitop3_b32 v2, v2, v13, s8 bitop3:0x36
	v_cndmask_b32_e64 v13, v2, 0, s[12:13]
	v_ashrrev_i32_e32 v2, 31, v14
	v_bitop3_b32 v2, v2, v14, s8 bitop3:0x36
	v_cndmask_b32_e64 v14, v2, 0, s[14:15]
	v_ashrrev_i32_e32 v2, 31, v15
	v_bitop3_b32 v2, v2, v15, s8 bitop3:0x36
	v_cndmask_b32_e64 v15, v2, 0, s[16:17]
	v_ashrrev_i32_e32 v2, 31, v16
	v_bitop3_b32 v2, v2, v16, s8 bitop3:0x36
	s_movk_i32 s8, 0xff
	v_cmp_gt_u32_e32 vcc, s63, v19
	v_cmp_lt_u32_e64 s[8:9], s8, v18
	s_and_b64 s[8:9], s[8:9], vcc
	v_cndmask_b32_e64 v16, v2, 0, s[18:19]
	v_cndmask_b32_e64 v2, 0, 1, s[8:9]
	v_cmp_ne_u32_e32 vcc, 0, v2
	s_ff1_i32_b64 s8, vcc
	s_cmp_lg_u64 vcc, 0
	s_cselect_b32 s8, s8, 0
	v_or_b32_e32 v2, v20, v6
	v_readlane_b32 s53, v5, s8
	v_readlane_b32 s48, v2, s8
	v_readlane_b32 s52, v21, s8
	s_cmp_gt_u32 s53, 64
	s_mov_b64 s[8:9], -1
	s_cbranch_scc1 .LBB0_784
	s_add_i32 s8, s48, 0xffffff80
	v_cvt_f32_i32_e32 v2, s8
	s_cmp_lg_u32 s48, 0
	s_cselect_b64 vcc, -1, 0
	s_add_i32 s8, s48, 0xffffff81
	v_mul_f32_e32 v2, 0.5, v2
	v_ashrrev_i32_e32 v3, 31, v2
	v_or_b32_e32 v3, 0x80000000, v3
	v_xor_b32_e32 v2, v3, v2
	v_cvt_f32_i32_e32 v3, s8
	s_cmpk_lg_i32 s48, 0xff
	v_cndmask_b32_e32 v2, 1, v2, vcc
	s_cselect_b64 vcc, -1, 0
	v_mul_f32_e32 v3, 0.5, v3
	v_ashrrev_i32_e32 v5, 31, v3
	v_or_b32_e32 v5, 0x80000000, v5
	v_xor_b32_e32 v3, v5, v3
	v_cndmask_b32_e32 v3, -1, v3, vcc
	v_sub_u32_e32 v3, v3, v2
	v_sub_u32_e32 v5, v4, v2
	v_cmp_lt_u32_e32 vcc, v5, v3
	s_and_saveexec_b64 s[8:9], vcc
	s_cbranch_execz .LBB0_750
	s_mov_b64 s[50:51], exec
	v_mbcnt_lo_u32_b32 v5, s50, 0
	v_mbcnt_hi_u32_b32 v5, s51, v5
	s_bcnt1_i32_b64 s50, s[50:51]
	s_mov_b32 s48, s100
	s_add_i32 s100, s100, s50
	v_add_u32_e32 v5, s48, v5
	v_and_b32_e32 v5, 63, v5
	v_lshl_add_u32 v5, v5, 2, s6
	ds_write_b32 v5, v4 offset:1032
.LBB0_750:
	s_or_b64 exec, exec, s[8:9]
	v_sub_u32_e32 v5, v10, v2
	v_cmp_lt_u32_e32 vcc, v5, v3
	s_and_saveexec_b64 s[8:9], vcc
	s_cbranch_execz .LBB0_754
	s_mov_b64 s[50:51], exec
	v_mbcnt_lo_u32_b32 v5, s50, 0
	v_mbcnt_hi_u32_b32 v5, s51, v5
	s_bcnt1_i32_b64 s50, s[50:51]
	s_mov_b32 s48, s100
	s_add_i32 s100, s100, s50
	v_add_u32_e32 v5, s48, v5
	v_and_b32_e32 v5, 63, v5
	v_lshl_add_u32 v5, v5, 2, s6
	ds_write_b32 v5, v10 offset:1032
.LBB0_754:
	s_or_b64 exec, exec, s[8:9]
	v_sub_u32_e32 v5, v11, v2
	v_cmp_lt_u32_e32 vcc, v5, v3
	s_and_saveexec_b64 s[8:9], vcc
	s_cbranch_execz .LBB0_758
	s_mov_b64 s[50:51], exec
	v_mbcnt_lo_u32_b32 v5, s50, 0
	v_mbcnt_hi_u32_b32 v5, s51, v5
	s_bcnt1_i32_b64 s50, s[50:51]
	s_mov_b32 s48, s100
	s_add_i32 s100, s100, s50
	v_add_u32_e32 v5, s48, v5
	v_and_b32_e32 v5, 63, v5
	v_lshl_add_u32 v5, v5, 2, s6
	ds_write_b32 v5, v11 offset:1032
.LBB0_758:
	s_or_b64 exec, exec, s[8:9]
	v_sub_u32_e32 v5, v12, v2
	v_cmp_lt_u32_e32 vcc, v5, v3
	s_and_saveexec_b64 s[8:9], vcc
	s_cbranch_execz .LBB0_762
	s_mov_b64 s[50:51], exec
	v_mbcnt_lo_u32_b32 v5, s50, 0
	v_mbcnt_hi_u32_b32 v5, s51, v5
	s_bcnt1_i32_b64 s50, s[50:51]
	s_mov_b32 s48, s100
	s_add_i32 s100, s100, s50
	v_add_u32_e32 v5, s48, v5
	v_and_b32_e32 v5, 63, v5
	v_lshl_add_u32 v5, v5, 2, s6
	ds_write_b32 v5, v12 offset:1032
.LBB0_762:
	s_or_b64 exec, exec, s[8:9]
	v_sub_u32_e32 v5, v13, v2
	v_cmp_lt_u32_e32 vcc, v5, v3
	s_and_saveexec_b64 s[8:9], vcc
	s_cbranch_execz .LBB0_766
	s_mov_b64 s[50:51], exec
	v_mbcnt_lo_u32_b32 v5, s50, 0
	v_mbcnt_hi_u32_b32 v5, s51, v5
	s_bcnt1_i32_b64 s50, s[50:51]
	s_mov_b32 s48, s100
	s_add_i32 s100, s100, s50
	v_add_u32_e32 v5, s48, v5
	v_and_b32_e32 v5, 63, v5
	v_lshl_add_u32 v5, v5, 2, s6
	ds_write_b32 v5, v13 offset:1032
.LBB0_766:
	s_or_b64 exec, exec, s[8:9]
	v_sub_u32_e32 v5, v14, v2
	v_cmp_lt_u32_e32 vcc, v5, v3
	s_and_saveexec_b64 s[8:9], vcc
	s_cbranch_execz .LBB0_770
	s_mov_b64 s[50:51], exec
	v_mbcnt_lo_u32_b32 v5, s50, 0
	v_mbcnt_hi_u32_b32 v5, s51, v5
	s_bcnt1_i32_b64 s50, s[50:51]
	s_mov_b32 s48, s100
	s_add_i32 s100, s100, s50
	v_add_u32_e32 v5, s48, v5
	v_and_b32_e32 v5, 63, v5
	v_lshl_add_u32 v5, v5, 2, s6
	ds_write_b32 v5, v14 offset:1032
.LBB0_770:
	s_or_b64 exec, exec, s[8:9]
	v_sub_u32_e32 v5, v15, v2
	v_cmp_lt_u32_e32 vcc, v5, v3
	s_and_saveexec_b64 s[8:9], vcc
	s_cbranch_execz .LBB0_774
	s_mov_b64 s[50:51], exec
	v_mbcnt_lo_u32_b32 v5, s50, 0
	v_mbcnt_hi_u32_b32 v5, s51, v5
	s_bcnt1_i32_b64 s50, s[50:51]
	s_mov_b32 s48, s100
	s_add_i32 s100, s100, s50
	v_add_u32_e32 v5, s48, v5
	v_and_b32_e32 v5, 63, v5
	v_lshl_add_u32 v5, v5, 2, s6
	ds_write_b32 v5, v15 offset:1032
.LBB0_774:
	s_or_b64 exec, exec, s[8:9]
	v_sub_u32_e32 v2, v16, v2
	v_cmp_lt_u32_e32 vcc, v2, v3
	s_and_saveexec_b64 s[8:9], vcc
	s_cbranch_execz .LBB0_778
	s_mov_b64 s[50:51], exec
	v_mbcnt_lo_u32_b32 v2, s50, 0
	v_mbcnt_hi_u32_b32 v2, s51, v2
	s_bcnt1_i32_b64 s50, s[50:51]
	s_mov_b32 s48, s100
	s_add_i32 s100, s100, s50
	v_add_u32_e32 v2, s48, v2
	v_and_b32_e32 v2, 63, v2
	v_lshl_add_u32 v2, v2, 2, s6
	ds_write_b32 v2, v16 offset:1032
